# v31 plus: residual-epilogue row-sum lane exchanges via v_permlane16_swap / v_permlane32_swap instead of ds_bpermute (80 sites)
# speedup vs baseline: 1.0025x; 1.0013x over previous
;     __device__ __forceinline__ void operator()(const f32x4 (&acc)[2][2][4][2], const Unit& u, int wr, int wc, int fr, int fq) const {
;     ...
;             u32x4 pre[2][4][2];
; #pragma unroll
;             for (int ai = 0; ai < 2; ++ai)
; #pragma unroll
;                 for (int m = 0; m < 4; ++m) { const size_t off = (size_t)(row0 + ai * HALF + m * 16) * 1024 + col0;
; #pragma unroll
;                     for (int bj = 0; bj < 2; ++bj) pre[ai][m][bj] = *(const u32x4*)(base16 + off + bj * HALF); }
;             asm volatile("" ::: "memory");
; #pragma unroll
;             for (int ai = 0; ai < 2; ++ai)
; #pragma unroll
;                 for (int m = 0; m < 4; ++m) {
;                     const int row = row0 + ai * HALF + m * 16; const size_t off = (size_t)row * 1024 + col0; float ss = 0.f;
; #pragma unroll
;                     for (int bj = 0; bj < 2; ++bj) { const u32x4 p = pre[ai][m][bj];
;                         const f32x4 b0 = {__uint_as_float(p.x << 16), __uint_as_float(p.x & 0xffff0000u), __uint_as_float(p.y << 16), __uint_as_float(p.y & 0xffff0000u)};
;                         const f32x4 b1 = {__uint_as_float(p.z << 16), __uint_as_float(p.z & 0xffff0000u), __uint_as_float(p.w << 16), __uint_as_float(p.w & 0xffff0000u)};
;                         const f32x4 v0 = b0 + acc[ai][bj][m][0] * alpha, v1 = b1 + acc[ai][bj][m][1] * alpha;
;                         store(off + bj * HALF, v0, v1, ss);
;                     }
;                     rowsum(row, ss, fq);
;                     if (m & 1) asm volatile("" ::: "memory");
;                 }
;         }
;     }
;     __device__ __forceinline__ void store(size_t o, const f32x4& v0, const f32x4& v1, float& ss) const {
;         if (out32) { *(f32x4*)(out32 + o) = v0; *(f32x4*)(out32 + o + 4) = v1; }
;         ss += (v0[0] * v0[0] + v0[1] * v0[1]) + (v0[2] * v0[2] + v0[3] * v0[3]) + (v1[0] * v1[0] + v1[1] * v1[1]) + (v1[2] * v1[2] + v1[3] * v1[3]);
;         if (hb) { u32x4 w; w.x = cvt_pk_bf16(v0[0], v0[1]); w.y = cvt_pk_bf16(v0[2], v0[3]); w.z = cvt_pk_bf16(v1[0], v1[1]); w.w = cvt_pk_bf16(v1[2], v1[3]); *(u32x4*)(hb + o) = w; }
;     }
;     __device__ __forceinline__ void rowsum(int row, float ss, int fq) const {
;         if (rowss_next) { ss += __shfl_xor(ss, 16); ss += __shfl_xor(ss, 32);
.LBB0_409:
	v_lshl_or_b32 v206, s58, 8, v245
	v_lshl_add_u32 v236, s57, 8, v243
	v_ashrrev_i32_e32 v207, 31, v206
	v_lshlrev_b64 v[238:239], 1, v[206:207]
	v_ashrrev_i32_e32 v237, 31, v236
	v_lshl_add_u64 v[116:117], s[14:15], 0, v[238:239]
	v_lshlrev_b64 v[240:241], 11, v[236:237]
	v_lshl_add_u64 v[112:113], v[116:117], 0, v[240:241]
	global_load_dwordx4 v[188:191], v[112:113], off
	global_load_dwordx4 v[184:187], v[112:113], off offset:256
	v_or_b32_e32 v232, 16, v236
	v_ashrrev_i32_e32 v233, 31, v232
	v_or_b32_e32 v228, 32, v236
	v_lshlrev_b64 v[234:235], 11, v[232:233]
	v_ashrrev_i32_e32 v229, 31, v228
	v_or_b32_e32 v224, 48, v236
	v_lshl_add_u64 v[112:113], v[116:117], 0, v[234:235]
	v_lshlrev_b64 v[230:231], 11, v[228:229]
	v_ashrrev_i32_e32 v225, 31, v224
	v_add_u32_e32 v220, 0x80, v236
	global_load_dwordx4 v[180:183], v[112:113], off
	global_load_dwordx4 v[176:179], v[112:113], off offset:256
	v_lshl_add_u64 v[112:113], v[116:117], 0, v[230:231]
	v_lshlrev_b64 v[226:227], 11, v[224:225]
	v_ashrrev_i32_e32 v221, 31, v220
	v_add_u32_e32 v216, 0x90, v236
	global_load_dwordx4 v[172:175], v[112:113], off
	global_load_dwordx4 v[168:171], v[112:113], off offset:256
	v_lshl_add_u64 v[112:113], v[116:117], 0, v[226:227]
	v_lshlrev_b64 v[222:223], 11, v[220:221]
	v_ashrrev_i32_e32 v217, 31, v216
	v_add_u32_e32 v212, 0xa0, v236
	v_add_u32_e32 v208, 0xb0, v236
	global_load_dwordx4 v[164:167], v[112:113], off
	global_load_dwordx4 v[160:163], v[112:113], off offset:256
	v_lshl_add_u64 v[112:113], v[116:117], 0, v[222:223]
	v_lshlrev_b64 v[218:219], 11, v[216:217]
	v_ashrrev_i32_e32 v213, 31, v212
	v_ashrrev_i32_e32 v209, 31, v208
	global_load_dwordx4 v[156:159], v[112:113], off
	global_load_dwordx4 v[152:155], v[112:113], off offset:256
	v_lshl_add_u64 v[112:113], v[116:117], 0, v[218:219]
	v_lshlrev_b64 v[214:215], 11, v[212:213]
	v_lshlrev_b64 v[210:211], 11, v[208:209]
	global_load_dwordx4 v[140:143], v[112:113], off
	global_load_dwordx4 v[136:139], v[112:113], off offset:256
	v_lshl_add_u64 v[112:113], v[116:117], 0, v[214:215]
	v_lshl_add_u64 v[116:117], v[116:117], 0, v[210:211]
	global_load_dwordx4 v[120:123], v[112:113], off
	s_nop 0
	global_load_dwordx4 v[112:115], v[112:113], off offset:256
	s_nop 0
	global_load_dwordx4 v[124:127], v[116:117], off
	s_nop 0
	global_load_dwordx4 v[116:119], v[116:117], off offset:256
	v_lshl_add_u64 v[240:241], s[14:15], 0, v[240:241]
	v_lshl_add_u64 v[238:239], v[240:241], 0, v[238:239]
	s_waitcnt vmcnt(0)
	v_lshlrev_b32_e32 v250, 16, v188
	v_and_b32_e32 v251, 0xffff0000, v188
	v_lshlrev_b32_e32 v188, 16, v189
	v_and_b32_e32 v189, 0xffff0000, v189
	v_lshlrev_b32_e32 v252, 16, v190
	v_and_b32_e32 v253, 0xffff0000, v190
	v_lshlrev_b32_e32 v190, 16, v191
	v_and_b32_e32 v191, 0xffff0000, v191
	v_pk_fma_f32 v[150:151], v[150:151], 0.5, v[188:189] op_sel_hi:[1,0,1]
	v_pk_fma_f32 v[148:149], v[148:149], 0.5, v[250:251] op_sel_hi:[1,0,1]
	v_pk_fma_f32 v[188:189], v[146:147], 0.5, v[190:191] op_sel_hi:[1,0,1]
	v_pk_fma_f32 v[190:191], v[144:145], 0.5, v[252:253] op_sel_hi:[1,0,1]
	v_cvt_pk_bf16_f32 v144, v148, v149
	v_cvt_pk_bf16_f32 v145, v150, v151
	s_nop 0
	v_cvt_pk_bf16_f32 v146, v190, v191
	v_cvt_pk_bf16_f32 v147, v188, v189
	global_store_dwordx4 v[238:239], v[144:147], off
	s_nop 1
	v_lshlrev_b32_e32 v144, 16, v184
	v_and_b32_e32 v145, 0xffff0000, v184
	v_lshlrev_b32_e32 v146, 16, v185
	v_and_b32_e32 v147, 0xffff0000, v185
	v_lshlrev_b32_e32 v184, 16, v186
	v_and_b32_e32 v185, 0xffff0000, v186
	v_lshlrev_b32_e32 v186, 16, v187
	v_and_b32_e32 v187, 0xffff0000, v187
	v_pk_fma_f32 v[134:135], v[134:135], 0.5, v[146:147] op_sel_hi:[1,0,1]
	v_pk_fma_f32 v[132:133], v[132:133], 0.5, v[144:145] op_sel_hi:[1,0,1]
	v_pk_fma_f32 v[144:145], v[130:131], 0.5, v[186:187] op_sel_hi:[1,0,1]
	v_pk_fma_f32 v[146:147], v[128:129], 0.5, v[184:185] op_sel_hi:[1,0,1]
	v_cvt_pk_bf16_f32 v128, v132, v133
	v_cvt_pk_bf16_f32 v129, v134, v135
	s_nop 0
	v_cvt_pk_bf16_f32 v130, v146, v147
	v_cvt_pk_bf16_f32 v131, v144, v145
	global_store_dwordx4 v[238:239], v[128:131], off offset:256
	s_nop 1
	v_mul_f32_e32 v130, v149, v149
	v_mul_f32_e32 v131, v151, v151
	v_fmac_f32_e32 v130, v148, v148
	v_fmac_f32_e32 v131, v150, v150
	v_mul_f32_e32 v129, v191, v191
	v_add_f32_e32 v130, v130, v131
	v_mul_f32_e32 v131, v133, v133
	v_mul_f32_e32 v128, v189, v189
	v_fmac_f32_e32 v129, v190, v190
	v_fmac_f32_e32 v131, v132, v132
	v_mul_f32_e32 v132, v135, v135
	v_fmac_f32_e32 v128, v188, v188
	v_add_f32_e32 v129, v129, v130
	v_mul_f32_e32 v130, v147, v147
	v_fmac_f32_e32 v132, v134, v134
	v_add_f32_e32 v128, v128, v129
	v_mul_f32_e32 v129, v145, v145
	v_fmac_f32_e32 v130, v146, v146
	v_add_f32_e32 v131, v131, v132
	v_fmac_f32_e32 v129, v144, v144
	v_add_f32_e32 v130, v130, v131
	v_add_f32_e32 v129, v129, v130
	v_and_b32_e32 v130, 64, v249
	v_add_f32_e32 v129, v128, v129
	v_xor_b32_e32 v128, 16, v249
	v_add_u32_e32 v131, 64, v130
	v_cmp_lt_i32_e32 vcc, v128, v131
	s_nop 1
	v_cndmask_b32_e32 v128, v249, v128, vcc
	v_lshlrev_b32_e32 v128, 2, v128
	v_mov_b32_e32 v130, v129
	s_nop 1
	v_permlane16_swap_b32_e32 v130, v129
	s_waitcnt lgkmcnt(0)
	v_add_f32_e32 v130, v129, v130
	v_xor_b32_e32 v129, 32, v249
	v_cmp_lt_i32_e32 vcc, v129, v131
	s_nop 1
	v_cndmask_b32_e32 v129, v249, v129, vcc
	v_lshlrev_b32_e32 v129, 2, v129
	v_mov_b32_e32 v131, v130
	s_nop 1
	v_permlane32_swap_b32_e32 v131, v130
	s_and_saveexec_b64 s[34:35], s[4:5]
	s_cbranch_execz .LBB0_411
	s_waitcnt lgkmcnt(0)
	v_add_f32_e32 v130, v130, v131
	v_mul_f32_e32 v130, 0x4b800000, v130
	v_trunc_f32_e32 v130, v130
	v_mul_f32_e32 v131, 0x2f800000, v130
	v_floor_f32_e32 v131, v131
	v_fmac_f32_e32 v130, 0xcf800000, v131
	v_cvt_u32_f32_e32 v130, v130
	v_cvt_u32_f32_e32 v131, v131
	v_lshl_add_u64 v[132:133], v[236:237], 3, s[16:17]
	global_atomic_add_x2 v[132:133], v[130:131], off
; __device__ __forceinline__ unsigned cvt_pk_bf16(float lo, float hi) { unsigned r; asm volatile("v_cvt_pk_bf16_f32 %0, %1, %2" : "=v"(r) : "v"(lo), "v"(hi)); return r; }
; __device__ __forceinline__ rss_t rss_fix(float ss) { return (rss_t)(ss * 16777216.0f); }
;     __device__ __forceinline__ void operator()(const f32x4 (&acc)[2][2][4][2], const Unit& u, int wr, int wc, int fr, int fq) const {
;     ...
;             for (int ai = 0; ai < 2; ++ai)
; #pragma unroll
;                 for (int m = 0; m < 4; ++m) {
;                     const int row = row0 + ai * HALF + m * 16; const size_t off = (size_t)row * 1024 + col0; float ss = 0.f;
; #pragma unroll
;                     for (int bj = 0; bj < 2; ++bj) { const u32x4 p = pre[ai][m][bj];
;                         const f32x4 b0 = {__uint_as_float(p.x << 16), __uint_as_float(p.x & 0xffff0000u), __uint_as_float(p.y << 16), __uint_as_float(p.y & 0xffff0000u)};
;                         const f32x4 b1 = {__uint_as_float(p.z << 16), __uint_as_float(p.z & 0xffff0000u), __uint_as_float(p.w << 16), __uint_as_float(p.w & 0xffff0000u)};
;                         const f32x4 v0 = b0 + acc[ai][bj][m][0] * alpha, v1 = b1 + acc[ai][bj][m][1] * alpha;
;                         store(off + bj * HALF, v0, v1, ss);
;                     }
;                     rowsum(row, ss, fq);
;                     if (m & 1) asm volatile("" ::: "memory");
;                 }
;         }
;     }
;     __device__ __forceinline__ void store(size_t o, const f32x4& v0, const f32x4& v1, float& ss) const {
;         if (out32) { *(f32x4*)(out32 + o) = v0; *(f32x4*)(out32 + o + 4) = v1; }
;         ss += (v0[0] * v0[0] + v0[1] * v0[1]) + (v0[2] * v0[2] + v0[3] * v0[3]) + (v1[0] * v1[0] + v1[1] * v1[1]) + (v1[2] * v1[2] + v1[3] * v1[3]);
;         if (hb) { u32x4 w; w.x = cvt_pk_bf16(v0[0], v0[1]); w.y = cvt_pk_bf16(v0[2], v0[3]); w.z = cvt_pk_bf16(v1[0], v1[1]); w.w = cvt_pk_bf16(v1[2], v1[3]); *(u32x4*)(hb + o) = w; }
;     }
;     __device__ __forceinline__ void rowsum(int row, float ss, int fq) const {
;         if (rowss_next) { ss += __shfl_xor(ss, 16); ss += __shfl_xor(ss, 32);
;             if (fq == 0) (void)__hip_atomic_fetch_add(rowss_next + row, rss_fix(ss), __ATOMIC_RELAXED, __HIP_MEMORY_SCOPE_AGENT); }
.LBB0_411:
	s_or_b64 exec, exec, s[34:35]
	v_lshlrev_b32_e32 v130, 16, v180
	s_waitcnt lgkmcnt(0)
	v_and_b32_e32 v131, 0xffff0000, v180
	v_lshlrev_b32_e32 v132, 16, v181
	v_and_b32_e32 v133, 0xffff0000, v181
	v_lshlrev_b32_e32 v134, 16, v182
	v_and_b32_e32 v135, 0xffff0000, v182
	v_lshlrev_b32_e32 v144, 16, v183
	v_and_b32_e32 v145, 0xffff0000, v183
	v_pk_fma_f32 v[110:111], v[110:111], 0.5, v[132:133] op_sel_hi:[1,0,1]
	v_pk_fma_f32 v[108:109], v[108:109], 0.5, v[130:131] op_sel_hi:[1,0,1]
	v_pk_fma_f32 v[132:133], v[104:105], 0.5, v[134:135] op_sel_hi:[1,0,1]
	v_lshlrev_b32_e32 v134, 16, v176
	v_and_b32_e32 v135, 0xffff0000, v176
	v_lshlrev_b32_e32 v148, 16, v179
	v_and_b32_e32 v149, 0xffff0000, v179
	v_pk_fma_f32 v[130:131], v[106:107], 0.5, v[144:145] op_sel_hi:[1,0,1]
	v_lshlrev_b32_e32 v144, 16, v177
	v_and_b32_e32 v145, 0xffff0000, v177
	v_lshlrev_b32_e32 v146, 16, v178
	v_and_b32_e32 v147, 0xffff0000, v178
	v_pk_fma_f32 v[100:101], v[100:101], 0.5, v[134:135] op_sel_hi:[1,0,1]
	v_pk_fma_f32 v[134:135], v[98:99], 0.5, v[148:149] op_sel_hi:[1,0,1]
	v_mul_f32_e32 v98, v109, v109
	v_mul_f32_e32 v99, v111, v111
	v_pk_fma_f32 v[102:103], v[102:103], 0.5, v[144:145] op_sel_hi:[1,0,1]
	v_pk_fma_f32 v[144:145], v[96:97], 0.5, v[146:147] op_sel_hi:[1,0,1]
	v_mul_f32_e32 v97, v133, v133
	v_fmac_f32_e32 v98, v108, v108
	v_fmac_f32_e32 v99, v110, v110
	v_cvt_pk_bf16_f32 v104, v108, v109
	v_mul_f32_e32 v96, v131, v131
	v_fmac_f32_e32 v97, v132, v132
	v_add_f32_e32 v98, v98, v99
	v_mul_f32_e32 v99, v101, v101
	v_mul_f32_e32 v108, v103, v103
	v_fmac_f32_e32 v96, v130, v130
	v_add_f32_e32 v97, v97, v98
	v_mul_f32_e32 v98, v145, v145
	v_fmac_f32_e32 v99, v100, v100
	v_fmac_f32_e32 v108, v102, v102
	v_add_f32_e32 v96, v96, v97
	v_mul_f32_e32 v97, v135, v135
	v_fmac_f32_e32 v98, v144, v144
	v_add_f32_e32 v99, v99, v108
	v_fmac_f32_e32 v97, v134, v134
	v_add_f32_e32 v98, v98, v99
	v_add_f32_e32 v97, v97, v98
	v_add_f32_e32 v99, v96, v97
	v_cvt_pk_bf16_f32 v105, v110, v111
	v_mov_b32_e32 v110, v99
	s_nop 1
	v_permlane16_swap_b32_e32 v110, v99
	v_lshl_add_u64 v[96:97], s[14:15], 0, v[234:235]
	v_lshl_add_u64 v[108:109], v[206:207], 1, v[96:97]
	v_cvt_pk_bf16_f32 v106, v132, v133
	v_cvt_pk_bf16_f32 v107, v130, v131
	s_waitcnt lgkmcnt(0)
	v_add_f32_e32 v96, v99, v110
	v_mov_b32_e32 v97, v96
	s_nop 1
	v_permlane32_swap_b32_e32 v97, v96
	global_store_dwordx4 v[108:109], v[104:107], off
	v_cvt_pk_bf16_f32 v98, v100, v101
	v_cvt_pk_bf16_f32 v99, v102, v103
	v_cvt_pk_bf16_f32 v100, v144, v145
	v_cvt_pk_bf16_f32 v101, v134, v135
	global_store_dwordx4 v[108:109], v[98:101], off offset:256
	s_and_saveexec_b64 s[34:35], s[4:5]
	s_cbranch_execz .LBB0_413
	s_waitcnt lgkmcnt(0)
	v_add_f32_e32 v96, v96, v97
	v_mul_f32_e32 v96, 0x4b800000, v96
	v_trunc_f32_e32 v96, v96
	v_mul_f32_e32 v97, 0x2f800000, v96
	v_floor_f32_e32 v97, v97
	v_fmac_f32_e32 v96, 0xcf800000, v97
	v_cvt_u32_f32_e32 v96, v96
	v_cvt_u32_f32_e32 v97, v97
	v_lshl_add_u64 v[98:99], v[232:233], 3, s[16:17]
	global_atomic_add_x2 v[98:99], v[96:97], off
.LBB0_413:
	s_or_b64 exec, exec, s[34:35]
	v_lshlrev_b32_e32 v96, 16, v172
	s_waitcnt lgkmcnt(0)
	v_and_b32_e32 v97, 0xffff0000, v172
	v_lshlrev_b32_e32 v98, 16, v173
	v_and_b32_e32 v99, 0xffff0000, v173
	v_lshlrev_b32_e32 v100, 16, v174
	v_and_b32_e32 v101, 0xffff0000, v174
	v_lshlrev_b32_e32 v102, 16, v175
	v_and_b32_e32 v103, 0xffff0000, v175
	v_pk_fma_f32 v[94:95], v[94:95], 0.5, v[98:99] op_sel_hi:[1,0,1]
	v_pk_fma_f32 v[92:93], v[92:93], 0.5, v[96:97] op_sel_hi:[1,0,1]
	v_pk_fma_f32 v[98:99], v[88:89], 0.5, v[100:101] op_sel_hi:[1,0,1]
	v_lshlrev_b32_e32 v100, 16, v168
	v_and_b32_e32 v101, 0xffff0000, v168
	v_lshlrev_b32_e32 v106, 16, v171
	v_and_b32_e32 v107, 0xffff0000, v171
	v_pk_fma_f32 v[96:97], v[90:91], 0.5, v[102:103] op_sel_hi:[1,0,1]
	v_lshlrev_b32_e32 v102, 16, v169
	v_and_b32_e32 v103, 0xffff0000, v169
	v_lshlrev_b32_e32 v104, 16, v170
	v_and_b32_e32 v105, 0xffff0000, v170
	v_pk_fma_f32 v[84:85], v[84:85], 0.5, v[100:101] op_sel_hi:[1,0,1]
	v_pk_fma_f32 v[100:101], v[82:83], 0.5, v[106:107] op_sel_hi:[1,0,1]
	v_mul_f32_e32 v82, v93, v93
	v_mul_f32_e32 v83, v95, v95
	v_pk_fma_f32 v[86:87], v[86:87], 0.5, v[102:103] op_sel_hi:[1,0,1]
	v_pk_fma_f32 v[102:103], v[80:81], 0.5, v[104:105] op_sel_hi:[1,0,1]
	v_mul_f32_e32 v81, v99, v99
	v_fmac_f32_e32 v82, v92, v92
	v_fmac_f32_e32 v83, v94, v94
	v_cvt_pk_bf16_f32 v88, v92, v93
	v_mul_f32_e32 v80, v97, v97
	v_fmac_f32_e32 v81, v98, v98
	v_add_f32_e32 v82, v82, v83
	v_mul_f32_e32 v83, v85, v85
	v_mul_f32_e32 v92, v87, v87
	v_fmac_f32_e32 v80, v96, v96
	v_add_f32_e32 v81, v81, v82
	v_mul_f32_e32 v82, v103, v103
	v_fmac_f32_e32 v83, v84, v84
	v_fmac_f32_e32 v92, v86, v86
	v_add_f32_e32 v80, v80, v81
	v_mul_f32_e32 v81, v101, v101
	v_fmac_f32_e32 v82, v102, v102
	v_add_f32_e32 v83, v83, v92
	v_fmac_f32_e32 v81, v100, v100
	v_add_f32_e32 v82, v82, v83
	v_add_f32_e32 v81, v81, v82
	v_add_f32_e32 v83, v80, v81
	v_cvt_pk_bf16_f32 v89, v94, v95
	v_mov_b32_e32 v94, v83
	s_nop 1
	v_permlane16_swap_b32_e32 v94, v83
	v_lshl_add_u64 v[80:81], s[14:15], 0, v[230:231]
	v_lshl_add_u64 v[92:93], v[206:207], 1, v[80:81]
	v_cvt_pk_bf16_f32 v90, v98, v99
	v_cvt_pk_bf16_f32 v91, v96, v97
	s_waitcnt lgkmcnt(0)
	v_add_f32_e32 v80, v83, v94
	v_mov_b32_e32 v81, v80
	s_nop 1
	v_permlane32_swap_b32_e32 v81, v80
	global_store_dwordx4 v[92:93], v[88:91], off
	v_cvt_pk_bf16_f32 v82, v84, v85
	v_cvt_pk_bf16_f32 v83, v86, v87
	v_cvt_pk_bf16_f32 v84, v102, v103
	v_cvt_pk_bf16_f32 v85, v100, v101
	global_store_dwordx4 v[92:93], v[82:85], off offset:256
	s_and_saveexec_b64 s[34:35], s[4:5]
	s_cbranch_execz .LBB0_415
	s_waitcnt lgkmcnt(0)
	v_add_f32_e32 v80, v80, v81
	v_mul_f32_e32 v80, 0x4b800000, v80
	v_trunc_f32_e32 v80, v80
	v_mul_f32_e32 v81, 0x2f800000, v80
	v_floor_f32_e32 v81, v81
	v_fmac_f32_e32 v80, 0xcf800000, v81
	v_cvt_u32_f32_e32 v80, v80
	v_cvt_u32_f32_e32 v81, v81
	v_lshl_add_u64 v[82:83], v[228:229], 3, s[16:17]
	global_atomic_add_x2 v[82:83], v[80:81], off
; __device__ __forceinline__ unsigned cvt_pk_bf16(float lo, float hi) { unsigned r; asm volatile("v_cvt_pk_bf16_f32 %0, %1, %2" : "=v"(r) : "v"(lo), "v"(hi)); return r; }
; __device__ __forceinline__ rss_t rss_fix(float ss) { return (rss_t)(ss * 16777216.0f); }
;     __device__ __forceinline__ void operator()(const f32x4 (&acc)[2][2][4][2], const Unit& u, int wr, int wc, int fr, int fq) const {
;     ...
;             for (int ai = 0; ai < 2; ++ai)
; #pragma unroll
;                 for (int m = 0; m < 4; ++m) {
;                     const int row = row0 + ai * HALF + m * 16; const size_t off = (size_t)row * 1024 + col0; float ss = 0.f;
; #pragma unroll
;                     for (int bj = 0; bj < 2; ++bj) { const u32x4 p = pre[ai][m][bj];
;                         const f32x4 b0 = {__uint_as_float(p.x << 16), __uint_as_float(p.x & 0xffff0000u), __uint_as_float(p.y << 16), __uint_as_float(p.y & 0xffff0000u)};
;                         const f32x4 b1 = {__uint_as_float(p.z << 16), __uint_as_float(p.z & 0xffff0000u), __uint_as_float(p.w << 16), __uint_as_float(p.w & 0xffff0000u)};
;                         const f32x4 v0 = b0 + acc[ai][bj][m][0] * alpha, v1 = b1 + acc[ai][bj][m][1] * alpha;
;                         store(off + bj * HALF, v0, v1, ss);
;                     }
;                     rowsum(row, ss, fq);
;                     if (m & 1) asm volatile("" ::: "memory");
;                 }
;         }
;     }
;     __device__ __forceinline__ void store(size_t o, const f32x4& v0, const f32x4& v1, float& ss) const {
;         if (out32) { *(f32x4*)(out32 + o) = v0; *(f32x4*)(out32 + o + 4) = v1; }
;         ss += (v0[0] * v0[0] + v0[1] * v0[1]) + (v0[2] * v0[2] + v0[3] * v0[3]) + (v1[0] * v1[0] + v1[1] * v1[1]) + (v1[2] * v1[2] + v1[3] * v1[3]);
;         if (hb) { u32x4 w; w.x = cvt_pk_bf16(v0[0], v0[1]); w.y = cvt_pk_bf16(v0[2], v0[3]); w.z = cvt_pk_bf16(v1[0], v1[1]); w.w = cvt_pk_bf16(v1[2], v1[3]); *(u32x4*)(hb + o) = w; }
;     }
;     __device__ __forceinline__ void rowsum(int row, float ss, int fq) const {
;         if (rowss_next) { ss += __shfl_xor(ss, 16); ss += __shfl_xor(ss, 32);
;             if (fq == 0) (void)__hip_atomic_fetch_add(rowss_next + row, rss_fix(ss), __ATOMIC_RELAXED, __HIP_MEMORY_SCOPE_AGENT); }
.LBB0_415:
	s_or_b64 exec, exec, s[34:35]
	v_lshlrev_b32_e32 v80, 16, v164
	s_waitcnt lgkmcnt(0)
	v_and_b32_e32 v81, 0xffff0000, v164
	v_lshlrev_b32_e32 v82, 16, v165
	v_and_b32_e32 v83, 0xffff0000, v165
	v_lshlrev_b32_e32 v84, 16, v166
	v_and_b32_e32 v85, 0xffff0000, v166
	v_lshlrev_b32_e32 v86, 16, v167
	v_and_b32_e32 v87, 0xffff0000, v167
	v_pk_fma_f32 v[78:79], v[78:79], 0.5, v[82:83] op_sel_hi:[1,0,1]
	v_pk_fma_f32 v[76:77], v[76:77], 0.5, v[80:81] op_sel_hi:[1,0,1]
	v_pk_fma_f32 v[82:83], v[72:73], 0.5, v[84:85] op_sel_hi:[1,0,1]
	v_lshlrev_b32_e32 v84, 16, v160
	v_and_b32_e32 v85, 0xffff0000, v160
	v_lshlrev_b32_e32 v90, 16, v163
	v_and_b32_e32 v91, 0xffff0000, v163
	v_pk_fma_f32 v[80:81], v[74:75], 0.5, v[86:87] op_sel_hi:[1,0,1]
	v_lshlrev_b32_e32 v86, 16, v161
	v_and_b32_e32 v87, 0xffff0000, v161
	v_lshlrev_b32_e32 v88, 16, v162
	v_and_b32_e32 v89, 0xffff0000, v162
	v_pk_fma_f32 v[68:69], v[68:69], 0.5, v[84:85] op_sel_hi:[1,0,1]
	v_pk_fma_f32 v[84:85], v[66:67], 0.5, v[90:91] op_sel_hi:[1,0,1]
	v_mul_f32_e32 v66, v77, v77
	v_mul_f32_e32 v67, v79, v79
	v_pk_fma_f32 v[70:71], v[70:71], 0.5, v[86:87] op_sel_hi:[1,0,1]
	v_pk_fma_f32 v[86:87], v[64:65], 0.5, v[88:89] op_sel_hi:[1,0,1]
	v_mul_f32_e32 v65, v83, v83
	v_fmac_f32_e32 v66, v76, v76
	v_fmac_f32_e32 v67, v78, v78
	v_cvt_pk_bf16_f32 v72, v76, v77
	v_mul_f32_e32 v64, v81, v81
	v_fmac_f32_e32 v65, v82, v82
	v_add_f32_e32 v66, v66, v67
	v_mul_f32_e32 v67, v69, v69
	v_mul_f32_e32 v76, v71, v71
	v_fmac_f32_e32 v64, v80, v80
	v_add_f32_e32 v65, v65, v66
	v_mul_f32_e32 v66, v87, v87
	v_fmac_f32_e32 v67, v68, v68
	v_fmac_f32_e32 v76, v70, v70
	v_add_f32_e32 v64, v64, v65
	v_mul_f32_e32 v65, v85, v85
	v_fmac_f32_e32 v66, v86, v86
	v_add_f32_e32 v67, v67, v76
	v_fmac_f32_e32 v65, v84, v84
	v_add_f32_e32 v66, v66, v67
	v_add_f32_e32 v65, v65, v66
	v_add_f32_e32 v67, v64, v65
	v_cvt_pk_bf16_f32 v73, v78, v79
	v_mov_b32_e32 v78, v67
	s_nop 1
	v_permlane16_swap_b32_e32 v78, v67
	v_lshl_add_u64 v[64:65], s[14:15], 0, v[226:227]
	v_lshl_add_u64 v[76:77], v[206:207], 1, v[64:65]
	v_cvt_pk_bf16_f32 v74, v82, v83
	v_cvt_pk_bf16_f32 v75, v80, v81
	s_waitcnt lgkmcnt(0)
	v_add_f32_e32 v64, v67, v78
	v_mov_b32_e32 v65, v64
	s_nop 1
	v_permlane32_swap_b32_e32 v65, v64
	global_store_dwordx4 v[76:77], v[72:75], off
	v_cvt_pk_bf16_f32 v66, v68, v69
	v_cvt_pk_bf16_f32 v67, v70, v71
	v_cvt_pk_bf16_f32 v68, v86, v87
	v_cvt_pk_bf16_f32 v69, v84, v85
	global_store_dwordx4 v[76:77], v[66:69], off offset:256
	s_and_saveexec_b64 s[34:35], s[4:5]
	s_cbranch_execz .LBB0_417
	s_waitcnt lgkmcnt(0)
	v_add_f32_e32 v64, v64, v65
	v_mul_f32_e32 v64, 0x4b800000, v64
	v_trunc_f32_e32 v64, v64
	v_mul_f32_e32 v65, 0x2f800000, v64
	v_floor_f32_e32 v65, v65
	v_fmac_f32_e32 v64, 0xcf800000, v65
	v_cvt_u32_f32_e32 v64, v64
	v_cvt_u32_f32_e32 v65, v65
	v_lshl_add_u64 v[66:67], v[224:225], 3, s[16:17]
	global_atomic_add_x2 v[66:67], v[64:65], off
.LBB0_417:
	s_or_b64 exec, exec, s[34:35]
	v_lshlrev_b32_e32 v64, 16, v156
	s_waitcnt lgkmcnt(0)
	v_and_b32_e32 v65, 0xffff0000, v156
	v_lshlrev_b32_e32 v66, 16, v157
	v_and_b32_e32 v67, 0xffff0000, v157
	v_lshlrev_b32_e32 v68, 16, v158
	v_and_b32_e32 v69, 0xffff0000, v158
	v_lshlrev_b32_e32 v70, 16, v159
	v_and_b32_e32 v71, 0xffff0000, v159
	v_pk_fma_f32 v[62:63], v[62:63], 0.5, v[66:67] op_sel_hi:[1,0,1]
	v_pk_fma_f32 v[60:61], v[60:61], 0.5, v[64:65] op_sel_hi:[1,0,1]
	v_pk_fma_f32 v[66:67], v[56:57], 0.5, v[68:69] op_sel_hi:[1,0,1]
	v_lshlrev_b32_e32 v68, 16, v152
	v_and_b32_e32 v69, 0xffff0000, v152
	v_lshlrev_b32_e32 v74, 16, v155
	v_and_b32_e32 v75, 0xffff0000, v155
	v_pk_fma_f32 v[64:65], v[58:59], 0.5, v[70:71] op_sel_hi:[1,0,1]
	v_lshlrev_b32_e32 v70, 16, v153
	v_and_b32_e32 v71, 0xffff0000, v153
	v_lshlrev_b32_e32 v72, 16, v154
	v_and_b32_e32 v73, 0xffff0000, v154
	v_pk_fma_f32 v[52:53], v[52:53], 0.5, v[68:69] op_sel_hi:[1,0,1]
	v_pk_fma_f32 v[68:69], v[50:51], 0.5, v[74:75] op_sel_hi:[1,0,1]
	v_mul_f32_e32 v50, v61, v61
	v_mul_f32_e32 v51, v63, v63
	v_pk_fma_f32 v[54:55], v[54:55], 0.5, v[70:71] op_sel_hi:[1,0,1]
	v_pk_fma_f32 v[70:71], v[48:49], 0.5, v[72:73] op_sel_hi:[1,0,1]
	v_mul_f32_e32 v49, v67, v67
	v_fmac_f32_e32 v50, v60, v60
	v_fmac_f32_e32 v51, v62, v62
	v_cvt_pk_bf16_f32 v56, v60, v61
	v_mul_f32_e32 v48, v65, v65
	v_fmac_f32_e32 v49, v66, v66
	v_add_f32_e32 v50, v50, v51
	v_mul_f32_e32 v51, v53, v53
	v_mul_f32_e32 v60, v55, v55
	v_fmac_f32_e32 v48, v64, v64
	v_add_f32_e32 v49, v49, v50
	v_mul_f32_e32 v50, v71, v71
	v_fmac_f32_e32 v51, v52, v52
	v_fmac_f32_e32 v60, v54, v54
	v_add_f32_e32 v48, v48, v49
	v_mul_f32_e32 v49, v69, v69
	v_fmac_f32_e32 v50, v70, v70
	v_add_f32_e32 v51, v51, v60
	v_fmac_f32_e32 v49, v68, v68
	v_add_f32_e32 v50, v50, v51
	v_add_f32_e32 v49, v49, v50
	v_add_f32_e32 v51, v48, v49
	v_cvt_pk_bf16_f32 v57, v62, v63
	v_mov_b32_e32 v62, v51
	s_nop 1
	v_permlane16_swap_b32_e32 v62, v51
	v_lshl_add_u64 v[48:49], s[14:15], 0, v[222:223]
	v_lshl_add_u64 v[60:61], v[206:207], 1, v[48:49]
	v_cvt_pk_bf16_f32 v58, v66, v67
	v_cvt_pk_bf16_f32 v59, v64, v65
	s_waitcnt lgkmcnt(0)
	v_add_f32_e32 v48, v51, v62
	v_mov_b32_e32 v49, v48
	s_nop 1
	v_permlane32_swap_b32_e32 v49, v48
	global_store_dwordx4 v[60:61], v[56:59], off
	v_cvt_pk_bf16_f32 v50, v52, v53
	v_cvt_pk_bf16_f32 v51, v54, v55
	v_cvt_pk_bf16_f32 v52, v70, v71
	v_cvt_pk_bf16_f32 v53, v68, v69
	global_store_dwordx4 v[60:61], v[50:53], off offset:256
	s_and_saveexec_b64 s[34:35], s[4:5]
	s_cbranch_execz .LBB0_419
	s_waitcnt lgkmcnt(0)
	v_add_f32_e32 v48, v48, v49
	v_mul_f32_e32 v48, 0x4b800000, v48
	v_trunc_f32_e32 v48, v48
	v_mul_f32_e32 v49, 0x2f800000, v48
	v_floor_f32_e32 v49, v49
	v_fmac_f32_e32 v48, 0xcf800000, v49
	v_cvt_u32_f32_e32 v48, v48
	v_cvt_u32_f32_e32 v49, v49
	v_lshl_add_u64 v[50:51], v[220:221], 3, s[16:17]
	global_atomic_add_x2 v[50:51], v[48:49], off
; __device__ __forceinline__ unsigned cvt_pk_bf16(float lo, float hi) { unsigned r; asm volatile("v_cvt_pk_bf16_f32 %0, %1, %2" : "=v"(r) : "v"(lo), "v"(hi)); return r; }
; __device__ __forceinline__ rss_t rss_fix(float ss) { return (rss_t)(ss * 16777216.0f); }
;     __device__ __forceinline__ void operator()(const f32x4 (&acc)[2][2][4][2], const Unit& u, int wr, int wc, int fr, int fq) const {
;     ...
;             for (int ai = 0; ai < 2; ++ai)
; #pragma unroll
;                 for (int m = 0; m < 4; ++m) {
;                     const int row = row0 + ai * HALF + m * 16; const size_t off = (size_t)row * 1024 + col0; float ss = 0.f;
; #pragma unroll
;                     for (int bj = 0; bj < 2; ++bj) { const u32x4 p = pre[ai][m][bj];
;                         const f32x4 b0 = {__uint_as_float(p.x << 16), __uint_as_float(p.x & 0xffff0000u), __uint_as_float(p.y << 16), __uint_as_float(p.y & 0xffff0000u)};
;                         const f32x4 b1 = {__uint_as_float(p.z << 16), __uint_as_float(p.z & 0xffff0000u), __uint_as_float(p.w << 16), __uint_as_float(p.w & 0xffff0000u)};
;                         const f32x4 v0 = b0 + acc[ai][bj][m][0] * alpha, v1 = b1 + acc[ai][bj][m][1] * alpha;
;                         store(off + bj * HALF, v0, v1, ss);
;                     }
;                     rowsum(row, ss, fq);
;                     if (m & 1) asm volatile("" ::: "memory");
;                 }
;         }
;     }
;     __device__ __forceinline__ void store(size_t o, const f32x4& v0, const f32x4& v1, float& ss) const {
;         if (out32) { *(f32x4*)(out32 + o) = v0; *(f32x4*)(out32 + o + 4) = v1; }
;         ss += (v0[0] * v0[0] + v0[1] * v0[1]) + (v0[2] * v0[2] + v0[3] * v0[3]) + (v1[0] * v1[0] + v1[1] * v1[1]) + (v1[2] * v1[2] + v1[3] * v1[3]);
;         if (hb) { u32x4 w; w.x = cvt_pk_bf16(v0[0], v0[1]); w.y = cvt_pk_bf16(v0[2], v0[3]); w.z = cvt_pk_bf16(v1[0], v1[1]); w.w = cvt_pk_bf16(v1[2], v1[3]); *(u32x4*)(hb + o) = w; }
;     }
;     __device__ __forceinline__ void rowsum(int row, float ss, int fq) const {
;         if (rowss_next) { ss += __shfl_xor(ss, 16); ss += __shfl_xor(ss, 32);
;             if (fq == 0) (void)__hip_atomic_fetch_add(rowss_next + row, rss_fix(ss), __ATOMIC_RELAXED, __HIP_MEMORY_SCOPE_AGENT); }
.LBB0_419:
	s_or_b64 exec, exec, s[34:35]
	v_lshlrev_b32_e32 v48, 16, v140
	s_waitcnt lgkmcnt(0)
	v_and_b32_e32 v49, 0xffff0000, v140
	v_lshlrev_b32_e32 v50, 16, v141
	v_and_b32_e32 v51, 0xffff0000, v141
	v_lshlrev_b32_e32 v52, 16, v142
	v_and_b32_e32 v53, 0xffff0000, v142
	v_lshlrev_b32_e32 v54, 16, v143
	v_and_b32_e32 v55, 0xffff0000, v143
	v_pk_fma_f32 v[46:47], v[46:47], 0.5, v[50:51] op_sel_hi:[1,0,1]
	v_pk_fma_f32 v[44:45], v[44:45], 0.5, v[48:49] op_sel_hi:[1,0,1]
	v_pk_fma_f32 v[50:51], v[40:41], 0.5, v[52:53] op_sel_hi:[1,0,1]
	v_lshlrev_b32_e32 v52, 16, v136
	v_and_b32_e32 v53, 0xffff0000, v136
	v_lshlrev_b32_e32 v58, 16, v139
	v_and_b32_e32 v59, 0xffff0000, v139
	v_pk_fma_f32 v[48:49], v[42:43], 0.5, v[54:55] op_sel_hi:[1,0,1]
	v_lshlrev_b32_e32 v54, 16, v137
	v_and_b32_e32 v55, 0xffff0000, v137
	v_lshlrev_b32_e32 v56, 16, v138
	v_and_b32_e32 v57, 0xffff0000, v138
	v_pk_fma_f32 v[36:37], v[36:37], 0.5, v[52:53] op_sel_hi:[1,0,1]
	v_pk_fma_f32 v[52:53], v[34:35], 0.5, v[58:59] op_sel_hi:[1,0,1]
	v_mul_f32_e32 v34, v45, v45
	v_mul_f32_e32 v35, v47, v47
	v_pk_fma_f32 v[38:39], v[38:39], 0.5, v[54:55] op_sel_hi:[1,0,1]
	v_pk_fma_f32 v[54:55], v[32:33], 0.5, v[56:57] op_sel_hi:[1,0,1]
	v_mul_f32_e32 v33, v51, v51
	v_fmac_f32_e32 v34, v44, v44
	v_fmac_f32_e32 v35, v46, v46
	v_cvt_pk_bf16_f32 v40, v44, v45
	v_mul_f32_e32 v32, v49, v49
	v_fmac_f32_e32 v33, v50, v50
	v_add_f32_e32 v34, v34, v35
	v_mul_f32_e32 v35, v37, v37
	v_mul_f32_e32 v44, v39, v39
	v_fmac_f32_e32 v32, v48, v48
	v_add_f32_e32 v33, v33, v34
	v_mul_f32_e32 v34, v55, v55
	v_fmac_f32_e32 v35, v36, v36
	v_fmac_f32_e32 v44, v38, v38
	v_add_f32_e32 v32, v32, v33
	v_mul_f32_e32 v33, v53, v53
	v_fmac_f32_e32 v34, v54, v54
	v_add_f32_e32 v35, v35, v44
	v_fmac_f32_e32 v33, v52, v52
	v_add_f32_e32 v34, v34, v35
	v_add_f32_e32 v33, v33, v34
	v_add_f32_e32 v35, v32, v33
	v_cvt_pk_bf16_f32 v41, v46, v47
	v_mov_b32_e32 v46, v35
	s_nop 1
	v_permlane16_swap_b32_e32 v46, v35
	v_lshl_add_u64 v[32:33], s[14:15], 0, v[218:219]
	v_lshl_add_u64 v[44:45], v[206:207], 1, v[32:33]
	v_cvt_pk_bf16_f32 v42, v50, v51
	v_cvt_pk_bf16_f32 v43, v48, v49
	s_waitcnt lgkmcnt(0)
	v_add_f32_e32 v32, v35, v46
	v_mov_b32_e32 v33, v32
	s_nop 1
	v_permlane32_swap_b32_e32 v33, v32
	global_store_dwordx4 v[44:45], v[40:43], off
	v_cvt_pk_bf16_f32 v34, v36, v37
	v_cvt_pk_bf16_f32 v35, v38, v39
	v_cvt_pk_bf16_f32 v36, v54, v55
	v_cvt_pk_bf16_f32 v37, v52, v53
	global_store_dwordx4 v[44:45], v[34:37], off offset:256
	s_and_saveexec_b64 s[34:35], s[4:5]
	s_cbranch_execz .LBB0_421
	s_waitcnt lgkmcnt(0)
	v_add_f32_e32 v32, v32, v33
	v_mul_f32_e32 v32, 0x4b800000, v32
	v_trunc_f32_e32 v32, v32
	v_mul_f32_e32 v33, 0x2f800000, v32
	v_floor_f32_e32 v33, v33
	v_fmac_f32_e32 v32, 0xcf800000, v33
	v_cvt_u32_f32_e32 v32, v32
	v_cvt_u32_f32_e32 v33, v33
	v_lshl_add_u64 v[34:35], v[216:217], 3, s[16:17]
	global_atomic_add_x2 v[34:35], v[32:33], off
; __device__ __forceinline__ unsigned cvt_pk_bf16(float lo, float hi) { unsigned r; asm volatile("v_cvt_pk_bf16_f32 %0, %1, %2" : "=v"(r) : "v"(lo), "v"(hi)); return r; }
; __device__ __forceinline__ rss_t rss_fix(float ss) { return (rss_t)(ss * 16777216.0f); }
;     __device__ __forceinline__ void operator()(const f32x4 (&acc)[2][2][4][2], const Unit& u, int wr, int wc, int fr, int fq) const {
;     ...
;             for (int ai = 0; ai < 2; ++ai)
; #pragma unroll
;                 for (int m = 0; m < 4; ++m) {
;                     const int row = row0 + ai * HALF + m * 16; const size_t off = (size_t)row * 1024 + col0; float ss = 0.f;
; #pragma unroll
;                     for (int bj = 0; bj < 2; ++bj) { const u32x4 p = pre[ai][m][bj];
;                         const f32x4 b0 = {__uint_as_float(p.x << 16), __uint_as_float(p.x & 0xffff0000u), __uint_as_float(p.y << 16), __uint_as_float(p.y & 0xffff0000u)};
;                         const f32x4 b1 = {__uint_as_float(p.z << 16), __uint_as_float(p.z & 0xffff0000u), __uint_as_float(p.w << 16), __uint_as_float(p.w & 0xffff0000u)};
;                         const f32x4 v0 = b0 + acc[ai][bj][m][0] * alpha, v1 = b1 + acc[ai][bj][m][1] * alpha;
;                         store(off + bj * HALF, v0, v1, ss);
;                     }
;                     rowsum(row, ss, fq);
;                     if (m & 1) asm volatile("" ::: "memory");
;                 }
;         }
;     }
;     __device__ __forceinline__ void store(size_t o, const f32x4& v0, const f32x4& v1, float& ss) const {
;         if (out32) { *(f32x4*)(out32 + o) = v0; *(f32x4*)(out32 + o + 4) = v1; }
;         ss += (v0[0] * v0[0] + v0[1] * v0[1]) + (v0[2] * v0[2] + v0[3] * v0[3]) + (v1[0] * v1[0] + v1[1] * v1[1]) + (v1[2] * v1[2] + v1[3] * v1[3]);
;         if (hb) { u32x4 w; w.x = cvt_pk_bf16(v0[0], v0[1]); w.y = cvt_pk_bf16(v0[2], v0[3]); w.z = cvt_pk_bf16(v1[0], v1[1]); w.w = cvt_pk_bf16(v1[2], v1[3]); *(u32x4*)(hb + o) = w; }
;     }
;     __device__ __forceinline__ void rowsum(int row, float ss, int fq) const {
;         if (rowss_next) { ss += __shfl_xor(ss, 16); ss += __shfl_xor(ss, 32);
;             if (fq == 0) (void)__hip_atomic_fetch_add(rowss_next + row, rss_fix(ss), __ATOMIC_RELAXED, __HIP_MEMORY_SCOPE_AGENT); }
.LBB0_421:
	s_or_b64 exec, exec, s[34:35]
	v_lshlrev_b32_e32 v32, 16, v120
	s_waitcnt lgkmcnt(0)
	v_and_b32_e32 v33, 0xffff0000, v120
	v_lshlrev_b32_e32 v34, 16, v121
	v_and_b32_e32 v35, 0xffff0000, v121
	v_lshlrev_b32_e32 v36, 16, v122
	v_and_b32_e32 v37, 0xffff0000, v122
	v_lshlrev_b32_e32 v38, 16, v123
	v_and_b32_e32 v39, 0xffff0000, v123
	v_pk_fma_f32 v[30:31], v[30:31], 0.5, v[34:35] op_sel_hi:[1,0,1]
	v_pk_fma_f32 v[28:29], v[28:29], 0.5, v[32:33] op_sel_hi:[1,0,1]
	v_pk_fma_f32 v[34:35], v[24:25], 0.5, v[36:37] op_sel_hi:[1,0,1]
	v_lshlrev_b32_e32 v36, 16, v112
	v_and_b32_e32 v37, 0xffff0000, v112
	v_lshlrev_b32_e32 v42, 16, v115
	v_and_b32_e32 v43, 0xffff0000, v115
	v_pk_fma_f32 v[32:33], v[26:27], 0.5, v[38:39] op_sel_hi:[1,0,1]
	v_lshlrev_b32_e32 v38, 16, v113
	v_and_b32_e32 v39, 0xffff0000, v113
	v_lshlrev_b32_e32 v40, 16, v114
	v_and_b32_e32 v41, 0xffff0000, v114
	v_pk_fma_f32 v[20:21], v[20:21], 0.5, v[36:37] op_sel_hi:[1,0,1]
	v_pk_fma_f32 v[36:37], v[18:19], 0.5, v[42:43] op_sel_hi:[1,0,1]
	v_mul_f32_e32 v18, v29, v29
	v_mul_f32_e32 v19, v31, v31
	v_pk_fma_f32 v[22:23], v[22:23], 0.5, v[38:39] op_sel_hi:[1,0,1]
	v_pk_fma_f32 v[38:39], v[16:17], 0.5, v[40:41] op_sel_hi:[1,0,1]
	v_mul_f32_e32 v17, v35, v35
	v_fmac_f32_e32 v18, v28, v28
	v_fmac_f32_e32 v19, v30, v30
	v_cvt_pk_bf16_f32 v24, v28, v29
	v_mul_f32_e32 v16, v33, v33
	v_fmac_f32_e32 v17, v34, v34
	v_add_f32_e32 v18, v18, v19
	v_mul_f32_e32 v19, v21, v21
	v_mul_f32_e32 v28, v23, v23
	v_fmac_f32_e32 v16, v32, v32
	v_add_f32_e32 v17, v17, v18
	v_mul_f32_e32 v18, v39, v39
	v_fmac_f32_e32 v19, v20, v20
	v_fmac_f32_e32 v28, v22, v22
	v_add_f32_e32 v16, v16, v17
	v_mul_f32_e32 v17, v37, v37
	v_fmac_f32_e32 v18, v38, v38
	v_add_f32_e32 v19, v19, v28
	v_fmac_f32_e32 v17, v36, v36
	v_add_f32_e32 v18, v18, v19
	v_add_f32_e32 v17, v17, v18
	v_add_f32_e32 v19, v16, v17
	v_cvt_pk_bf16_f32 v25, v30, v31
	v_mov_b32_e32 v30, v19
	s_nop 1
	v_permlane16_swap_b32_e32 v30, v19
	v_lshl_add_u64 v[16:17], s[14:15], 0, v[214:215]
	v_lshl_add_u64 v[28:29], v[206:207], 1, v[16:17]
	v_cvt_pk_bf16_f32 v26, v34, v35
	v_cvt_pk_bf16_f32 v27, v32, v33
	s_waitcnt lgkmcnt(0)
	v_add_f32_e32 v16, v19, v30
	v_mov_b32_e32 v17, v16
	s_nop 1
	v_permlane32_swap_b32_e32 v17, v16
	global_store_dwordx4 v[28:29], v[24:27], off
	v_cvt_pk_bf16_f32 v18, v20, v21
	v_cvt_pk_bf16_f32 v19, v22, v23
	v_cvt_pk_bf16_f32 v20, v38, v39
	v_cvt_pk_bf16_f32 v21, v36, v37
	global_store_dwordx4 v[28:29], v[18:21], off offset:256
	s_and_saveexec_b64 s[34:35], s[4:5]
	s_cbranch_execz .LBB0_423
	s_waitcnt lgkmcnt(0)
	v_add_f32_e32 v16, v16, v17
	v_mul_f32_e32 v16, 0x4b800000, v16
	v_trunc_f32_e32 v16, v16
	v_mul_f32_e32 v17, 0x2f800000, v16
	v_floor_f32_e32 v17, v17
	v_fmac_f32_e32 v16, 0xcf800000, v17
	v_cvt_u32_f32_e32 v16, v16
	v_cvt_u32_f32_e32 v17, v17
	v_lshl_add_u64 v[18:19], v[212:213], 3, s[16:17]
	global_atomic_add_x2 v[18:19], v[16:17], off
.LBB0_423:
	s_or_b64 exec, exec, s[34:35]
	v_lshlrev_b32_e32 v16, 16, v124
	s_waitcnt lgkmcnt(0)
	v_and_b32_e32 v17, 0xffff0000, v124
	v_lshlrev_b32_e32 v18, 16, v125
	v_and_b32_e32 v19, 0xffff0000, v125
	v_lshlrev_b32_e32 v20, 16, v126
	v_and_b32_e32 v21, 0xffff0000, v126
	v_lshlrev_b32_e32 v22, 16, v127
	v_and_b32_e32 v23, 0xffff0000, v127
	v_pk_fma_f32 v[14:15], v[14:15], 0.5, v[18:19] op_sel_hi:[1,0,1]
	v_pk_fma_f32 v[12:13], v[12:13], 0.5, v[16:17] op_sel_hi:[1,0,1]
	v_pk_fma_f32 v[18:19], v[8:9], 0.5, v[20:21] op_sel_hi:[1,0,1]
	v_lshlrev_b32_e32 v20, 16, v116
	v_and_b32_e32 v21, 0xffff0000, v116
	v_lshlrev_b32_e32 v26, 16, v119
	v_and_b32_e32 v27, 0xffff0000, v119
	v_pk_fma_f32 v[16:17], v[10:11], 0.5, v[22:23] op_sel_hi:[1,0,1]
	v_lshlrev_b32_e32 v22, 16, v117
	v_and_b32_e32 v23, 0xffff0000, v117
	v_lshlrev_b32_e32 v24, 16, v118
	v_and_b32_e32 v25, 0xffff0000, v118
	v_pk_fma_f32 v[4:5], v[4:5], 0.5, v[20:21] op_sel_hi:[1,0,1]
	v_pk_fma_f32 v[20:21], v[2:3], 0.5, v[26:27] op_sel_hi:[1,0,1]
	v_mul_f32_e32 v2, v13, v13
	v_mul_f32_e32 v3, v15, v15
	v_pk_fma_f32 v[6:7], v[6:7], 0.5, v[22:23] op_sel_hi:[1,0,1]
	v_pk_fma_f32 v[22:23], v[0:1], 0.5, v[24:25] op_sel_hi:[1,0,1]
	v_mul_f32_e32 v1, v19, v19
	v_fmac_f32_e32 v2, v12, v12
	v_fmac_f32_e32 v3, v14, v14
	v_cvt_pk_bf16_f32 v8, v12, v13
	v_mul_f32_e32 v0, v17, v17
	v_fmac_f32_e32 v1, v18, v18
	v_add_f32_e32 v2, v2, v3
	v_mul_f32_e32 v3, v5, v5
	v_mul_f32_e32 v12, v7, v7
	v_fmac_f32_e32 v0, v16, v16
	v_add_f32_e32 v1, v1, v2
	v_mul_f32_e32 v2, v23, v23
	v_fmac_f32_e32 v3, v4, v4
	v_fmac_f32_e32 v12, v6, v6
	v_add_f32_e32 v0, v0, v1
	v_mul_f32_e32 v1, v21, v21
	v_fmac_f32_e32 v2, v22, v22
	v_add_f32_e32 v3, v3, v12
	v_fmac_f32_e32 v1, v20, v20
	v_add_f32_e32 v2, v2, v3
	v_add_f32_e32 v1, v1, v2
	v_add_f32_e32 v3, v0, v1
	v_cvt_pk_bf16_f32 v9, v14, v15
	v_mov_b32_e32 v14, v3
	s_nop 1
	v_permlane16_swap_b32_e32 v14, v3
	v_lshl_add_u64 v[0:1], s[14:15], 0, v[210:211]
	v_lshl_add_u64 v[12:13], v[206:207], 1, v[0:1]
	v_cvt_pk_bf16_f32 v10, v18, v19
	v_cvt_pk_bf16_f32 v11, v16, v17
	s_waitcnt lgkmcnt(0)
	v_add_f32_e32 v0, v3, v14
	v_mov_b32_e32 v1, v0
	s_nop 1
	v_permlane32_swap_b32_e32 v1, v0
	global_store_dwordx4 v[12:13], v[8:11], off
	v_cvt_pk_bf16_f32 v2, v4, v5
	v_cvt_pk_bf16_f32 v3, v6, v7
	v_cvt_pk_bf16_f32 v4, v22, v23
	v_cvt_pk_bf16_f32 v5, v20, v21
	global_store_dwordx4 v[12:13], v[2:5], off offset:256
	s_and_saveexec_b64 s[34:35], s[4:5]
	s_cbranch_execz .LBB0_425
	s_waitcnt lgkmcnt(0)
	v_add_f32_e32 v0, v0, v1
	v_mul_f32_e32 v0, 0x4b800000, v0
	v_trunc_f32_e32 v0, v0
	v_mul_f32_e32 v1, 0x2f800000, v0
	v_floor_f32_e32 v1, v1
	v_fmac_f32_e32 v0, 0xcf800000, v1
	v_cvt_u32_f32_e32 v0, v0
	v_cvt_u32_f32_e32 v1, v1
	v_lshl_add_u64 v[2:3], v[208:209], 3, s[16:17]
	global_atomic_add_x2 v[2:3], v[0:1], off

;     __device__ __forceinline__ void operator()(const f32x4 (&acc)[2][2][4][2], const Unit& u, int wr, int wc, int fr, int fq) const {
;     ...
;             u32x4 pre[2][4][2];
; #pragma unroll
;             for (int ai = 0; ai < 2; ++ai)
; #pragma unroll
;                 for (int m = 0; m < 4; ++m) { const size_t off = (size_t)(row0 + ai * HALF + m * 16) * 1024 + col0;
; #pragma unroll
;                     for (int bj = 0; bj < 2; ++bj) pre[ai][m][bj] = *(const u32x4*)(base16 + off + bj * HALF); }
;             asm volatile("" ::: "memory");
; #pragma unroll
;             for (int ai = 0; ai < 2; ++ai)
; #pragma unroll
;                 for (int m = 0; m < 4; ++m) {
;                     const int row = row0 + ai * HALF + m * 16; const size_t off = (size_t)row * 1024 + col0; float ss = 0.f;
; #pragma unroll
;                     for (int bj = 0; bj < 2; ++bj) { const u32x4 p = pre[ai][m][bj];
;                         const f32x4 b0 = {__uint_as_float(p.x << 16), __uint_as_float(p.x & 0xffff0000u), __uint_as_float(p.y << 16), __uint_as_float(p.y & 0xffff0000u)};
;                         const f32x4 b1 = {__uint_as_float(p.z << 16), __uint_as_float(p.z & 0xffff0000u), __uint_as_float(p.w << 16), __uint_as_float(p.w & 0xffff0000u)};
;                         const f32x4 v0 = b0 + acc[ai][bj][m][0] * alpha, v1 = b1 + acc[ai][bj][m][1] * alpha;
;                         store(off + bj * HALF, v0, v1, ss);
;                     }
;                     rowsum(row, ss, fq);
;                     if (m & 1) asm volatile("" ::: "memory");
;                 }
;         }
;     }
;     __device__ __forceinline__ void store(size_t o, const f32x4& v0, const f32x4& v1, float& ss) const {
;         if (out32) { *(f32x4*)(out32 + o) = v0; *(f32x4*)(out32 + o + 4) = v1; }
;         ss += (v0[0] * v0[0] + v0[1] * v0[1]) + (v0[2] * v0[2] + v0[3] * v0[3]) + (v1[0] * v1[0] + v1[1] * v1[1]) + (v1[2] * v1[2] + v1[3] * v1[3]);
;         if (hb) { u32x4 w; w.x = cvt_pk_bf16(v0[0], v0[1]); w.y = cvt_pk_bf16(v0[2], v0[3]); w.z = cvt_pk_bf16(v1[0], v1[1]); w.w = cvt_pk_bf16(v1[2], v1[3]); *(u32x4*)(hb + o) = w; }
;     }
;     __device__ __forceinline__ void rowsum(int row, float ss, int fq) const {
;         if (rowss_next) { ss += __shfl_xor(ss, 16); ss += __shfl_xor(ss, 32);
.LBB0_1015:
	v_lshl_or_b32 v206, s40, 8, v245
	v_lshl_add_u32 v236, s38, 8, v243
	v_ashrrev_i32_e32 v207, 31, v206
	v_lshlrev_b64 v[238:239], 1, v[206:207]
	v_ashrrev_i32_e32 v237, 31, v236
	v_lshl_add_u64 v[116:117], s[12:13], 0, v[238:239]
	v_lshlrev_b64 v[240:241], 11, v[236:237]
	v_lshl_add_u64 v[112:113], v[116:117], 0, v[240:241]
	global_load_dwordx4 v[188:191], v[112:113], off
	global_load_dwordx4 v[184:187], v[112:113], off offset:256
	v_or_b32_e32 v232, 16, v236
	v_ashrrev_i32_e32 v233, 31, v232
	v_or_b32_e32 v228, 32, v236
	v_lshlrev_b64 v[234:235], 11, v[232:233]
	v_ashrrev_i32_e32 v229, 31, v228
	v_or_b32_e32 v224, 48, v236
	v_lshl_add_u64 v[112:113], v[116:117], 0, v[234:235]
	v_lshlrev_b64 v[230:231], 11, v[228:229]
	v_ashrrev_i32_e32 v225, 31, v224
	v_add_u32_e32 v220, 0x80, v236
	global_load_dwordx4 v[180:183], v[112:113], off
	global_load_dwordx4 v[176:179], v[112:113], off offset:256
	v_lshl_add_u64 v[112:113], v[116:117], 0, v[230:231]
	v_lshlrev_b64 v[226:227], 11, v[224:225]
	v_ashrrev_i32_e32 v221, 31, v220
	v_add_u32_e32 v216, 0x90, v236
	global_load_dwordx4 v[172:175], v[112:113], off
	global_load_dwordx4 v[168:171], v[112:113], off offset:256
	v_lshl_add_u64 v[112:113], v[116:117], 0, v[226:227]
	v_lshlrev_b64 v[222:223], 11, v[220:221]
	v_ashrrev_i32_e32 v217, 31, v216
	v_add_u32_e32 v212, 0xa0, v236
	v_add_u32_e32 v208, 0xb0, v236
	global_load_dwordx4 v[164:167], v[112:113], off
	global_load_dwordx4 v[160:163], v[112:113], off offset:256
	v_lshl_add_u64 v[112:113], v[116:117], 0, v[222:223]
	v_lshlrev_b64 v[218:219], 11, v[216:217]
	v_ashrrev_i32_e32 v213, 31, v212
	v_ashrrev_i32_e32 v209, 31, v208
	global_load_dwordx4 v[156:159], v[112:113], off
	global_load_dwordx4 v[152:155], v[112:113], off offset:256
	v_lshl_add_u64 v[112:113], v[116:117], 0, v[218:219]
	v_lshlrev_b64 v[214:215], 11, v[212:213]
	v_lshlrev_b64 v[210:211], 11, v[208:209]
	global_load_dwordx4 v[140:143], v[112:113], off
	global_load_dwordx4 v[136:139], v[112:113], off offset:256
	v_lshl_add_u64 v[112:113], v[116:117], 0, v[214:215]
	v_lshl_add_u64 v[116:117], v[116:117], 0, v[210:211]
	global_load_dwordx4 v[120:123], v[112:113], off
	s_nop 0
	global_load_dwordx4 v[112:115], v[112:113], off offset:256
	s_nop 0
	global_load_dwordx4 v[124:127], v[116:117], off
	s_nop 0
	global_load_dwordx4 v[116:119], v[116:117], off offset:256
	v_lshl_add_u64 v[240:241], s[12:13], 0, v[240:241]
	v_lshl_add_u64 v[238:239], v[240:241], 0, v[238:239]
	s_waitcnt vmcnt(0)
	v_lshlrev_b32_e32 v250, 16, v188
	v_and_b32_e32 v251, 0xffff0000, v188
	v_lshlrev_b32_e32 v188, 16, v189
	v_and_b32_e32 v189, 0xffff0000, v189
	v_lshlrev_b32_e32 v252, 16, v190
	v_and_b32_e32 v253, 0xffff0000, v190
	v_lshlrev_b32_e32 v190, 16, v191
	v_and_b32_e32 v191, 0xffff0000, v191
	v_pk_add_f32 v[150:151], v[150:151], v[188:189]
	v_pk_add_f32 v[148:149], v[148:149], v[250:251]
	v_pk_add_f32 v[188:189], v[146:147], v[190:191]
	v_pk_add_f32 v[190:191], v[144:145], v[252:253]
	v_cvt_pk_bf16_f32 v144, v148, v149
	v_cvt_pk_bf16_f32 v145, v150, v151
	s_nop 0
	v_cvt_pk_bf16_f32 v146, v190, v191
	v_cvt_pk_bf16_f32 v147, v188, v189
	global_store_dwordx4 v[238:239], v[144:147], off
	s_nop 1
	v_lshlrev_b32_e32 v144, 16, v184
	v_and_b32_e32 v145, 0xffff0000, v184
	v_lshlrev_b32_e32 v146, 16, v185
	v_and_b32_e32 v147, 0xffff0000, v185
	v_lshlrev_b32_e32 v184, 16, v186
	v_and_b32_e32 v185, 0xffff0000, v186
	v_lshlrev_b32_e32 v186, 16, v187
	v_and_b32_e32 v187, 0xffff0000, v187
	v_pk_add_f32 v[134:135], v[134:135], v[146:147]
	v_pk_add_f32 v[132:133], v[132:133], v[144:145]
	v_pk_add_f32 v[144:145], v[130:131], v[186:187]
	v_pk_add_f32 v[146:147], v[128:129], v[184:185]
	v_cvt_pk_bf16_f32 v128, v132, v133
	v_cvt_pk_bf16_f32 v129, v134, v135
	s_nop 0
	v_cvt_pk_bf16_f32 v130, v146, v147
	v_cvt_pk_bf16_f32 v131, v144, v145
	global_store_dwordx4 v[238:239], v[128:131], off offset:256
	s_nop 1
	v_mul_f32_e32 v130, v149, v149
	v_mul_f32_e32 v131, v151, v151
	v_fmac_f32_e32 v130, v148, v148
	v_fmac_f32_e32 v131, v150, v150
	v_mul_f32_e32 v129, v191, v191
	v_add_f32_e32 v130, v130, v131
	v_mul_f32_e32 v131, v133, v133
	v_mul_f32_e32 v128, v189, v189
	v_fmac_f32_e32 v129, v190, v190
	v_fmac_f32_e32 v131, v132, v132
	v_mul_f32_e32 v132, v135, v135
	v_fmac_f32_e32 v128, v188, v188
	v_add_f32_e32 v129, v129, v130
	v_mul_f32_e32 v130, v147, v147
	v_fmac_f32_e32 v132, v134, v134
	v_add_f32_e32 v128, v128, v129
	v_mul_f32_e32 v129, v145, v145
	v_fmac_f32_e32 v130, v146, v146
	v_add_f32_e32 v131, v131, v132
	v_fmac_f32_e32 v129, v144, v144
	v_add_f32_e32 v130, v130, v131
	v_add_f32_e32 v129, v129, v130
	v_and_b32_e32 v130, 64, v249
	v_add_f32_e32 v129, v128, v129
	v_xor_b32_e32 v128, 16, v249
	v_add_u32_e32 v131, 64, v130
	v_cmp_lt_i32_e32 vcc, v128, v131
	s_nop 1
	v_cndmask_b32_e32 v128, v249, v128, vcc
	v_lshlrev_b32_e32 v128, 2, v128
	v_mov_b32_e32 v130, v129
	s_nop 1
	v_permlane16_swap_b32_e32 v130, v129
	s_waitcnt lgkmcnt(0)
	v_add_f32_e32 v130, v129, v130
	v_xor_b32_e32 v129, 32, v249
	v_cmp_lt_i32_e32 vcc, v129, v131
	s_nop 1
	v_cndmask_b32_e32 v129, v249, v129, vcc
	v_lshlrev_b32_e32 v129, 2, v129
	v_mov_b32_e32 v131, v130
	s_nop 1
	v_permlane32_swap_b32_e32 v131, v130
	s_and_saveexec_b64 s[38:39], s[4:5]
	s_cbranch_execz .LBB0_1017
	s_waitcnt lgkmcnt(0)
	v_add_f32_e32 v130, v130, v131
	v_mul_f32_e32 v130, 0x4b800000, v130
	v_trunc_f32_e32 v130, v130
	v_mul_f32_e32 v131, 0x2f800000, v130
	v_floor_f32_e32 v131, v131
	v_fmac_f32_e32 v130, 0xcf800000, v131
	v_cvt_u32_f32_e32 v130, v130
	v_cvt_u32_f32_e32 v131, v131
	v_lshl_add_u64 v[132:133], v[236:237], 3, s[14:15]
	global_atomic_add_x2 v[132:133], v[130:131], off
; __device__ __forceinline__ unsigned cvt_pk_bf16(float lo, float hi) { unsigned r; asm volatile("v_cvt_pk_bf16_f32 %0, %1, %2" : "=v"(r) : "v"(lo), "v"(hi)); return r; }
; __device__ __forceinline__ rss_t rss_fix(float ss) { return (rss_t)(ss * 16777216.0f); }
;     __device__ __forceinline__ void operator()(const f32x4 (&acc)[2][2][4][2], const Unit& u, int wr, int wc, int fr, int fq) const {
;     ...
;             for (int ai = 0; ai < 2; ++ai)
; #pragma unroll
;                 for (int m = 0; m < 4; ++m) {
;                     const int row = row0 + ai * HALF + m * 16; const size_t off = (size_t)row * 1024 + col0; float ss = 0.f;
; #pragma unroll
;                     for (int bj = 0; bj < 2; ++bj) { const u32x4 p = pre[ai][m][bj];
;                         const f32x4 b0 = {__uint_as_float(p.x << 16), __uint_as_float(p.x & 0xffff0000u), __uint_as_float(p.y << 16), __uint_as_float(p.y & 0xffff0000u)};
;                         const f32x4 b1 = {__uint_as_float(p.z << 16), __uint_as_float(p.z & 0xffff0000u), __uint_as_float(p.w << 16), __uint_as_float(p.w & 0xffff0000u)};
;                         const f32x4 v0 = b0 + acc[ai][bj][m][0] * alpha, v1 = b1 + acc[ai][bj][m][1] * alpha;
;                         store(off + bj * HALF, v0, v1, ss);
;                     }
;                     rowsum(row, ss, fq);
;                     if (m & 1) asm volatile("" ::: "memory");
;                 }
;         }
;     }
;     __device__ __forceinline__ void store(size_t o, const f32x4& v0, const f32x4& v1, float& ss) const {
;         if (out32) { *(f32x4*)(out32 + o) = v0; *(f32x4*)(out32 + o + 4) = v1; }
;         ss += (v0[0] * v0[0] + v0[1] * v0[1]) + (v0[2] * v0[2] + v0[3] * v0[3]) + (v1[0] * v1[0] + v1[1] * v1[1]) + (v1[2] * v1[2] + v1[3] * v1[3]);
;         if (hb) { u32x4 w; w.x = cvt_pk_bf16(v0[0], v0[1]); w.y = cvt_pk_bf16(v0[2], v0[3]); w.z = cvt_pk_bf16(v1[0], v1[1]); w.w = cvt_pk_bf16(v1[2], v1[3]); *(u32x4*)(hb + o) = w; }
;     }
;     __device__ __forceinline__ void rowsum(int row, float ss, int fq) const {
;         if (rowss_next) { ss += __shfl_xor(ss, 16); ss += __shfl_xor(ss, 32);
;             if (fq == 0) (void)__hip_atomic_fetch_add(rowss_next + row, rss_fix(ss), __ATOMIC_RELAXED, __HIP_MEMORY_SCOPE_AGENT); }
.LBB0_1017:
	s_or_b64 exec, exec, s[38:39]
	v_lshlrev_b32_e32 v130, 16, v180
	s_waitcnt lgkmcnt(0)
	v_and_b32_e32 v131, 0xffff0000, v180
	v_lshlrev_b32_e32 v132, 16, v181
	v_and_b32_e32 v133, 0xffff0000, v181
	v_lshlrev_b32_e32 v134, 16, v182
	v_and_b32_e32 v135, 0xffff0000, v182
	v_lshlrev_b32_e32 v144, 16, v183
	v_and_b32_e32 v145, 0xffff0000, v183
	v_pk_add_f32 v[110:111], v[110:111], v[132:133]
	v_pk_add_f32 v[108:109], v[108:109], v[130:131]
	v_pk_add_f32 v[132:133], v[104:105], v[134:135]
	v_lshlrev_b32_e32 v134, 16, v176
	v_and_b32_e32 v135, 0xffff0000, v176
	v_lshlrev_b32_e32 v148, 16, v179
	v_and_b32_e32 v149, 0xffff0000, v179
	v_pk_add_f32 v[130:131], v[106:107], v[144:145]
	v_lshlrev_b32_e32 v144, 16, v177
	v_and_b32_e32 v145, 0xffff0000, v177
	v_lshlrev_b32_e32 v146, 16, v178
	v_and_b32_e32 v147, 0xffff0000, v178
	v_pk_add_f32 v[100:101], v[100:101], v[134:135]
	v_pk_add_f32 v[134:135], v[98:99], v[148:149]
	v_mul_f32_e32 v98, v109, v109
	v_mul_f32_e32 v99, v111, v111
	v_pk_add_f32 v[102:103], v[102:103], v[144:145]
	v_pk_add_f32 v[144:145], v[96:97], v[146:147]
	v_mul_f32_e32 v97, v133, v133
	v_fmac_f32_e32 v98, v108, v108
	v_fmac_f32_e32 v99, v110, v110
	v_cvt_pk_bf16_f32 v104, v108, v109
	v_mul_f32_e32 v96, v131, v131
	v_fmac_f32_e32 v97, v132, v132
	v_add_f32_e32 v98, v98, v99
	v_mul_f32_e32 v99, v101, v101
	v_mul_f32_e32 v108, v103, v103
	v_fmac_f32_e32 v96, v130, v130
	v_add_f32_e32 v97, v97, v98
	v_mul_f32_e32 v98, v145, v145
	v_fmac_f32_e32 v99, v100, v100
	v_fmac_f32_e32 v108, v102, v102
	v_add_f32_e32 v96, v96, v97
	v_mul_f32_e32 v97, v135, v135
	v_fmac_f32_e32 v98, v144, v144
	v_add_f32_e32 v99, v99, v108
	v_fmac_f32_e32 v97, v134, v134
	v_add_f32_e32 v98, v98, v99
	v_add_f32_e32 v97, v97, v98
	v_add_f32_e32 v99, v96, v97
	v_cvt_pk_bf16_f32 v105, v110, v111
	v_mov_b32_e32 v110, v99
	s_nop 1
	v_permlane16_swap_b32_e32 v110, v99
	v_lshl_add_u64 v[96:97], s[12:13], 0, v[234:235]
	v_lshl_add_u64 v[108:109], v[206:207], 1, v[96:97]
	v_cvt_pk_bf16_f32 v106, v132, v133
	v_cvt_pk_bf16_f32 v107, v130, v131
	s_waitcnt lgkmcnt(0)
	v_add_f32_e32 v96, v99, v110
	v_mov_b32_e32 v97, v96
	s_nop 1
	v_permlane32_swap_b32_e32 v97, v96
	global_store_dwordx4 v[108:109], v[104:107], off
	v_cvt_pk_bf16_f32 v98, v100, v101
	v_cvt_pk_bf16_f32 v99, v102, v103
	v_cvt_pk_bf16_f32 v100, v144, v145
	v_cvt_pk_bf16_f32 v101, v134, v135
	global_store_dwordx4 v[108:109], v[98:101], off offset:256
	s_and_saveexec_b64 s[38:39], s[4:5]
	s_cbranch_execz .LBB0_1019
	s_waitcnt lgkmcnt(0)
	v_add_f32_e32 v96, v96, v97
	v_mul_f32_e32 v96, 0x4b800000, v96
	v_trunc_f32_e32 v96, v96
	v_mul_f32_e32 v97, 0x2f800000, v96
	v_floor_f32_e32 v97, v97
	v_fmac_f32_e32 v96, 0xcf800000, v97
	v_cvt_u32_f32_e32 v96, v96
	v_cvt_u32_f32_e32 v97, v97
	v_lshl_add_u64 v[98:99], v[232:233], 3, s[14:15]
	global_atomic_add_x2 v[98:99], v[96:97], off
.LBB0_1019:
	s_or_b64 exec, exec, s[38:39]
	v_lshlrev_b32_e32 v96, 16, v172
	s_waitcnt lgkmcnt(0)
	v_and_b32_e32 v97, 0xffff0000, v172
	v_lshlrev_b32_e32 v98, 16, v173
	v_and_b32_e32 v99, 0xffff0000, v173
	v_lshlrev_b32_e32 v100, 16, v174
	v_and_b32_e32 v101, 0xffff0000, v174
	v_lshlrev_b32_e32 v102, 16, v175
	v_and_b32_e32 v103, 0xffff0000, v175
	v_pk_add_f32 v[94:95], v[94:95], v[98:99]
	v_pk_add_f32 v[92:93], v[92:93], v[96:97]
	v_pk_add_f32 v[98:99], v[88:89], v[100:101]
	v_lshlrev_b32_e32 v100, 16, v168
	v_and_b32_e32 v101, 0xffff0000, v168
	v_lshlrev_b32_e32 v106, 16, v171
	v_and_b32_e32 v107, 0xffff0000, v171
	v_pk_add_f32 v[96:97], v[90:91], v[102:103]
	v_lshlrev_b32_e32 v102, 16, v169
	v_and_b32_e32 v103, 0xffff0000, v169
	v_lshlrev_b32_e32 v104, 16, v170
	v_and_b32_e32 v105, 0xffff0000, v170
	v_pk_add_f32 v[84:85], v[84:85], v[100:101]
	v_pk_add_f32 v[100:101], v[82:83], v[106:107]
	v_mul_f32_e32 v82, v93, v93
	v_mul_f32_e32 v83, v95, v95
	v_pk_add_f32 v[86:87], v[86:87], v[102:103]
	v_pk_add_f32 v[102:103], v[80:81], v[104:105]
	v_mul_f32_e32 v81, v99, v99
	v_fmac_f32_e32 v82, v92, v92
	v_fmac_f32_e32 v83, v94, v94
	v_cvt_pk_bf16_f32 v88, v92, v93
	v_mul_f32_e32 v80, v97, v97
	v_fmac_f32_e32 v81, v98, v98
	v_add_f32_e32 v82, v82, v83
	v_mul_f32_e32 v83, v85, v85
	v_mul_f32_e32 v92, v87, v87
	v_fmac_f32_e32 v80, v96, v96
	v_add_f32_e32 v81, v81, v82
	v_mul_f32_e32 v82, v103, v103
	v_fmac_f32_e32 v83, v84, v84
	v_fmac_f32_e32 v92, v86, v86
	v_add_f32_e32 v80, v80, v81
	v_mul_f32_e32 v81, v101, v101
	v_fmac_f32_e32 v82, v102, v102
	v_add_f32_e32 v83, v83, v92
	v_fmac_f32_e32 v81, v100, v100
	v_add_f32_e32 v82, v82, v83
	v_add_f32_e32 v81, v81, v82
	v_add_f32_e32 v83, v80, v81
	v_cvt_pk_bf16_f32 v89, v94, v95
	v_mov_b32_e32 v94, v83
	s_nop 1
	v_permlane16_swap_b32_e32 v94, v83
	v_lshl_add_u64 v[80:81], s[12:13], 0, v[230:231]
	v_lshl_add_u64 v[92:93], v[206:207], 1, v[80:81]
	v_cvt_pk_bf16_f32 v90, v98, v99
	v_cvt_pk_bf16_f32 v91, v96, v97
	s_waitcnt lgkmcnt(0)
	v_add_f32_e32 v80, v83, v94
	v_mov_b32_e32 v81, v80
	s_nop 1
	v_permlane32_swap_b32_e32 v81, v80
	global_store_dwordx4 v[92:93], v[88:91], off
	v_cvt_pk_bf16_f32 v82, v84, v85
	v_cvt_pk_bf16_f32 v83, v86, v87
	v_cvt_pk_bf16_f32 v84, v102, v103
	v_cvt_pk_bf16_f32 v85, v100, v101
	global_store_dwordx4 v[92:93], v[82:85], off offset:256
	s_and_saveexec_b64 s[38:39], s[4:5]
	s_cbranch_execz .LBB0_1021
	s_waitcnt lgkmcnt(0)
	v_add_f32_e32 v80, v80, v81
	v_mul_f32_e32 v80, 0x4b800000, v80
	v_trunc_f32_e32 v80, v80
	v_mul_f32_e32 v81, 0x2f800000, v80
	v_floor_f32_e32 v81, v81
	v_fmac_f32_e32 v80, 0xcf800000, v81
	v_cvt_u32_f32_e32 v80, v80
	v_cvt_u32_f32_e32 v81, v81
	v_lshl_add_u64 v[82:83], v[228:229], 3, s[14:15]
	global_atomic_add_x2 v[82:83], v[80:81], off
; __device__ __forceinline__ unsigned cvt_pk_bf16(float lo, float hi) { unsigned r; asm volatile("v_cvt_pk_bf16_f32 %0, %1, %2" : "=v"(r) : "v"(lo), "v"(hi)); return r; }
; __device__ __forceinline__ rss_t rss_fix(float ss) { return (rss_t)(ss * 16777216.0f); }
;     __device__ __forceinline__ void operator()(const f32x4 (&acc)[2][2][4][2], const Unit& u, int wr, int wc, int fr, int fq) const {
;     ...
;             for (int ai = 0; ai < 2; ++ai)
; #pragma unroll
;                 for (int m = 0; m < 4; ++m) {
;                     const int row = row0 + ai * HALF + m * 16; const size_t off = (size_t)row * 1024 + col0; float ss = 0.f;
; #pragma unroll
;                     for (int bj = 0; bj < 2; ++bj) { const u32x4 p = pre[ai][m][bj];
;                         const f32x4 b0 = {__uint_as_float(p.x << 16), __uint_as_float(p.x & 0xffff0000u), __uint_as_float(p.y << 16), __uint_as_float(p.y & 0xffff0000u)};
;                         const f32x4 b1 = {__uint_as_float(p.z << 16), __uint_as_float(p.z & 0xffff0000u), __uint_as_float(p.w << 16), __uint_as_float(p.w & 0xffff0000u)};
;                         const f32x4 v0 = b0 + acc[ai][bj][m][0] * alpha, v1 = b1 + acc[ai][bj][m][1] * alpha;
;                         store(off + bj * HALF, v0, v1, ss);
;                     }
;                     rowsum(row, ss, fq);
;                     if (m & 1) asm volatile("" ::: "memory");
;                 }
;         }
;     }
;     __device__ __forceinline__ void store(size_t o, const f32x4& v0, const f32x4& v1, float& ss) const {
;         if (out32) { *(f32x4*)(out32 + o) = v0; *(f32x4*)(out32 + o + 4) = v1; }
;         ss += (v0[0] * v0[0] + v0[1] * v0[1]) + (v0[2] * v0[2] + v0[3] * v0[3]) + (v1[0] * v1[0] + v1[1] * v1[1]) + (v1[2] * v1[2] + v1[3] * v1[3]);
;         if (hb) { u32x4 w; w.x = cvt_pk_bf16(v0[0], v0[1]); w.y = cvt_pk_bf16(v0[2], v0[3]); w.z = cvt_pk_bf16(v1[0], v1[1]); w.w = cvt_pk_bf16(v1[2], v1[3]); *(u32x4*)(hb + o) = w; }
;     }
;     __device__ __forceinline__ void rowsum(int row, float ss, int fq) const {
;         if (rowss_next) { ss += __shfl_xor(ss, 16); ss += __shfl_xor(ss, 32);
;             if (fq == 0) (void)__hip_atomic_fetch_add(rowss_next + row, rss_fix(ss), __ATOMIC_RELAXED, __HIP_MEMORY_SCOPE_AGENT); }
.LBB0_1021:
	s_or_b64 exec, exec, s[38:39]
	v_lshlrev_b32_e32 v80, 16, v164
	s_waitcnt lgkmcnt(0)
	v_and_b32_e32 v81, 0xffff0000, v164
	v_lshlrev_b32_e32 v82, 16, v165
	v_and_b32_e32 v83, 0xffff0000, v165
	v_lshlrev_b32_e32 v84, 16, v166
	v_and_b32_e32 v85, 0xffff0000, v166
	v_lshlrev_b32_e32 v86, 16, v167
	v_and_b32_e32 v87, 0xffff0000, v167
	v_pk_add_f32 v[78:79], v[78:79], v[82:83]
	v_pk_add_f32 v[76:77], v[76:77], v[80:81]
	v_pk_add_f32 v[82:83], v[72:73], v[84:85]
	v_lshlrev_b32_e32 v84, 16, v160
	v_and_b32_e32 v85, 0xffff0000, v160
	v_lshlrev_b32_e32 v90, 16, v163
	v_and_b32_e32 v91, 0xffff0000, v163
	v_pk_add_f32 v[80:81], v[74:75], v[86:87]
	v_lshlrev_b32_e32 v86, 16, v161
	v_and_b32_e32 v87, 0xffff0000, v161
	v_lshlrev_b32_e32 v88, 16, v162
	v_and_b32_e32 v89, 0xffff0000, v162
	v_pk_add_f32 v[68:69], v[68:69], v[84:85]
	v_pk_add_f32 v[84:85], v[66:67], v[90:91]
	v_mul_f32_e32 v66, v77, v77
	v_mul_f32_e32 v67, v79, v79
	v_pk_add_f32 v[70:71], v[70:71], v[86:87]
	v_pk_add_f32 v[86:87], v[64:65], v[88:89]
	v_mul_f32_e32 v65, v83, v83
	v_fmac_f32_e32 v66, v76, v76
	v_fmac_f32_e32 v67, v78, v78
	v_cvt_pk_bf16_f32 v72, v76, v77
	v_mul_f32_e32 v64, v81, v81
	v_fmac_f32_e32 v65, v82, v82
	v_add_f32_e32 v66, v66, v67
	v_mul_f32_e32 v67, v69, v69
	v_mul_f32_e32 v76, v71, v71
	v_fmac_f32_e32 v64, v80, v80
	v_add_f32_e32 v65, v65, v66
	v_mul_f32_e32 v66, v87, v87
	v_fmac_f32_e32 v67, v68, v68
	v_fmac_f32_e32 v76, v70, v70
	v_add_f32_e32 v64, v64, v65
	v_mul_f32_e32 v65, v85, v85
	v_fmac_f32_e32 v66, v86, v86
	v_add_f32_e32 v67, v67, v76
	v_fmac_f32_e32 v65, v84, v84
	v_add_f32_e32 v66, v66, v67
	v_add_f32_e32 v65, v65, v66
	v_add_f32_e32 v67, v64, v65
	v_cvt_pk_bf16_f32 v73, v78, v79
	v_mov_b32_e32 v78, v67
	s_nop 1
	v_permlane16_swap_b32_e32 v78, v67
	v_lshl_add_u64 v[64:65], s[12:13], 0, v[226:227]
	v_lshl_add_u64 v[76:77], v[206:207], 1, v[64:65]
	v_cvt_pk_bf16_f32 v74, v82, v83
	v_cvt_pk_bf16_f32 v75, v80, v81
	s_waitcnt lgkmcnt(0)
	v_add_f32_e32 v64, v67, v78
	v_mov_b32_e32 v65, v64
	s_nop 1
	v_permlane32_swap_b32_e32 v65, v64
	global_store_dwordx4 v[76:77], v[72:75], off
	v_cvt_pk_bf16_f32 v66, v68, v69
	v_cvt_pk_bf16_f32 v67, v70, v71
	v_cvt_pk_bf16_f32 v68, v86, v87
	v_cvt_pk_bf16_f32 v69, v84, v85
	global_store_dwordx4 v[76:77], v[66:69], off offset:256
	s_and_saveexec_b64 s[38:39], s[4:5]
	s_cbranch_execz .LBB0_1023
	s_waitcnt lgkmcnt(0)
	v_add_f32_e32 v64, v64, v65
	v_mul_f32_e32 v64, 0x4b800000, v64
	v_trunc_f32_e32 v64, v64
	v_mul_f32_e32 v65, 0x2f800000, v64
	v_floor_f32_e32 v65, v65
	v_fmac_f32_e32 v64, 0xcf800000, v65
	v_cvt_u32_f32_e32 v64, v64
	v_cvt_u32_f32_e32 v65, v65
	v_lshl_add_u64 v[66:67], v[224:225], 3, s[14:15]
	global_atomic_add_x2 v[66:67], v[64:65], off
.LBB0_1023:
	s_or_b64 exec, exec, s[38:39]
	v_lshlrev_b32_e32 v64, 16, v156
	s_waitcnt lgkmcnt(0)
	v_and_b32_e32 v65, 0xffff0000, v156
	v_lshlrev_b32_e32 v66, 16, v157
	v_and_b32_e32 v67, 0xffff0000, v157
	v_lshlrev_b32_e32 v68, 16, v158
	v_and_b32_e32 v69, 0xffff0000, v158
	v_lshlrev_b32_e32 v70, 16, v159
	v_and_b32_e32 v71, 0xffff0000, v159
	v_pk_add_f32 v[62:63], v[62:63], v[66:67]
	v_pk_add_f32 v[60:61], v[60:61], v[64:65]
	v_pk_add_f32 v[66:67], v[56:57], v[68:69]
	v_lshlrev_b32_e32 v68, 16, v152
	v_and_b32_e32 v69, 0xffff0000, v152
	v_lshlrev_b32_e32 v74, 16, v155
	v_and_b32_e32 v75, 0xffff0000, v155
	v_pk_add_f32 v[64:65], v[58:59], v[70:71]
	v_lshlrev_b32_e32 v70, 16, v153
	v_and_b32_e32 v71, 0xffff0000, v153
	v_lshlrev_b32_e32 v72, 16, v154
	v_and_b32_e32 v73, 0xffff0000, v154
	v_pk_add_f32 v[52:53], v[52:53], v[68:69]
	v_pk_add_f32 v[68:69], v[50:51], v[74:75]
	v_mul_f32_e32 v50, v61, v61
	v_mul_f32_e32 v51, v63, v63
	v_pk_add_f32 v[54:55], v[54:55], v[70:71]
	v_pk_add_f32 v[70:71], v[48:49], v[72:73]
	v_mul_f32_e32 v49, v67, v67
	v_fmac_f32_e32 v50, v60, v60
	v_fmac_f32_e32 v51, v62, v62
	v_cvt_pk_bf16_f32 v56, v60, v61
	v_mul_f32_e32 v48, v65, v65
	v_fmac_f32_e32 v49, v66, v66
	v_add_f32_e32 v50, v50, v51
	v_mul_f32_e32 v51, v53, v53
	v_mul_f32_e32 v60, v55, v55
	v_fmac_f32_e32 v48, v64, v64
	v_add_f32_e32 v49, v49, v50
	v_mul_f32_e32 v50, v71, v71
	v_fmac_f32_e32 v51, v52, v52
	v_fmac_f32_e32 v60, v54, v54
	v_add_f32_e32 v48, v48, v49
	v_mul_f32_e32 v49, v69, v69
	v_fmac_f32_e32 v50, v70, v70
	v_add_f32_e32 v51, v51, v60
	v_fmac_f32_e32 v49, v68, v68
	v_add_f32_e32 v50, v50, v51
	v_add_f32_e32 v49, v49, v50
	v_add_f32_e32 v51, v48, v49
	v_cvt_pk_bf16_f32 v57, v62, v63
	v_mov_b32_e32 v62, v51
	s_nop 1
	v_permlane16_swap_b32_e32 v62, v51
	v_lshl_add_u64 v[48:49], s[12:13], 0, v[222:223]
	v_lshl_add_u64 v[60:61], v[206:207], 1, v[48:49]
	v_cvt_pk_bf16_f32 v58, v66, v67
	v_cvt_pk_bf16_f32 v59, v64, v65
	s_waitcnt lgkmcnt(0)
	v_add_f32_e32 v48, v51, v62
	v_mov_b32_e32 v49, v48
	s_nop 1
	v_permlane32_swap_b32_e32 v49, v48
	global_store_dwordx4 v[60:61], v[56:59], off
	v_cvt_pk_bf16_f32 v50, v52, v53
	v_cvt_pk_bf16_f32 v51, v54, v55
	v_cvt_pk_bf16_f32 v52, v70, v71
	v_cvt_pk_bf16_f32 v53, v68, v69
	global_store_dwordx4 v[60:61], v[50:53], off offset:256
	s_and_saveexec_b64 s[38:39], s[4:5]
	s_cbranch_execz .LBB0_1025
	s_waitcnt lgkmcnt(0)
	v_add_f32_e32 v48, v48, v49
	v_mul_f32_e32 v48, 0x4b800000, v48
	v_trunc_f32_e32 v48, v48
	v_mul_f32_e32 v49, 0x2f800000, v48
	v_floor_f32_e32 v49, v49
	v_fmac_f32_e32 v48, 0xcf800000, v49
	v_cvt_u32_f32_e32 v48, v48
	v_cvt_u32_f32_e32 v49, v49
	v_lshl_add_u64 v[50:51], v[220:221], 3, s[14:15]
	global_atomic_add_x2 v[50:51], v[48:49], off
; __device__ __forceinline__ unsigned cvt_pk_bf16(float lo, float hi) { unsigned r; asm volatile("v_cvt_pk_bf16_f32 %0, %1, %2" : "=v"(r) : "v"(lo), "v"(hi)); return r; }
; __device__ __forceinline__ rss_t rss_fix(float ss) { return (rss_t)(ss * 16777216.0f); }
;     __device__ __forceinline__ void operator()(const f32x4 (&acc)[2][2][4][2], const Unit& u, int wr, int wc, int fr, int fq) const {
;     ...
;             for (int ai = 0; ai < 2; ++ai)
; #pragma unroll
;                 for (int m = 0; m < 4; ++m) {
;                     const int row = row0 + ai * HALF + m * 16; const size_t off = (size_t)row * 1024 + col0; float ss = 0.f;
; #pragma unroll
;                     for (int bj = 0; bj < 2; ++bj) { const u32x4 p = pre[ai][m][bj];
;                         const f32x4 b0 = {__uint_as_float(p.x << 16), __uint_as_float(p.x & 0xffff0000u), __uint_as_float(p.y << 16), __uint_as_float(p.y & 0xffff0000u)};
;                         const f32x4 b1 = {__uint_as_float(p.z << 16), __uint_as_float(p.z & 0xffff0000u), __uint_as_float(p.w << 16), __uint_as_float(p.w & 0xffff0000u)};
;                         const f32x4 v0 = b0 + acc[ai][bj][m][0] * alpha, v1 = b1 + acc[ai][bj][m][1] * alpha;
;                         store(off + bj * HALF, v0, v1, ss);
;                     }
;                     rowsum(row, ss, fq);
;                     if (m & 1) asm volatile("" ::: "memory");
;                 }
;         }
;     }
;     __device__ __forceinline__ void store(size_t o, const f32x4& v0, const f32x4& v1, float& ss) const {
;         if (out32) { *(f32x4*)(out32 + o) = v0; *(f32x4*)(out32 + o + 4) = v1; }
;         ss += (v0[0] * v0[0] + v0[1] * v0[1]) + (v0[2] * v0[2] + v0[3] * v0[3]) + (v1[0] * v1[0] + v1[1] * v1[1]) + (v1[2] * v1[2] + v1[3] * v1[3]);
;         if (hb) { u32x4 w; w.x = cvt_pk_bf16(v0[0], v0[1]); w.y = cvt_pk_bf16(v0[2], v0[3]); w.z = cvt_pk_bf16(v1[0], v1[1]); w.w = cvt_pk_bf16(v1[2], v1[3]); *(u32x4*)(hb + o) = w; }
;     }
;     __device__ __forceinline__ void rowsum(int row, float ss, int fq) const {
;         if (rowss_next) { ss += __shfl_xor(ss, 16); ss += __shfl_xor(ss, 32);
;             if (fq == 0) (void)__hip_atomic_fetch_add(rowss_next + row, rss_fix(ss), __ATOMIC_RELAXED, __HIP_MEMORY_SCOPE_AGENT); }
.LBB0_1025:
	s_or_b64 exec, exec, s[38:39]
	v_lshlrev_b32_e32 v48, 16, v140
	s_waitcnt lgkmcnt(0)
	v_and_b32_e32 v49, 0xffff0000, v140
	v_lshlrev_b32_e32 v50, 16, v141
	v_and_b32_e32 v51, 0xffff0000, v141
	v_lshlrev_b32_e32 v52, 16, v142
	v_and_b32_e32 v53, 0xffff0000, v142
	v_lshlrev_b32_e32 v54, 16, v143
	v_and_b32_e32 v55, 0xffff0000, v143
	v_pk_add_f32 v[46:47], v[46:47], v[50:51]
	v_pk_add_f32 v[44:45], v[44:45], v[48:49]
	v_pk_add_f32 v[50:51], v[40:41], v[52:53]
	v_lshlrev_b32_e32 v52, 16, v136
	v_and_b32_e32 v53, 0xffff0000, v136
	v_lshlrev_b32_e32 v58, 16, v139
	v_and_b32_e32 v59, 0xffff0000, v139
	v_pk_add_f32 v[48:49], v[42:43], v[54:55]
	v_lshlrev_b32_e32 v54, 16, v137
	v_and_b32_e32 v55, 0xffff0000, v137
	v_lshlrev_b32_e32 v56, 16, v138
	v_and_b32_e32 v57, 0xffff0000, v138
	v_pk_add_f32 v[36:37], v[36:37], v[52:53]
	v_pk_add_f32 v[52:53], v[34:35], v[58:59]
	v_mul_f32_e32 v34, v45, v45
	v_mul_f32_e32 v35, v47, v47
	v_pk_add_f32 v[38:39], v[38:39], v[54:55]
	v_pk_add_f32 v[54:55], v[32:33], v[56:57]
	v_mul_f32_e32 v33, v51, v51
	v_fmac_f32_e32 v34, v44, v44
	v_fmac_f32_e32 v35, v46, v46
	v_cvt_pk_bf16_f32 v40, v44, v45
	v_mul_f32_e32 v32, v49, v49
	v_fmac_f32_e32 v33, v50, v50
	v_add_f32_e32 v34, v34, v35
	v_mul_f32_e32 v35, v37, v37
	v_mul_f32_e32 v44, v39, v39
	v_fmac_f32_e32 v32, v48, v48
	v_add_f32_e32 v33, v33, v34
	v_mul_f32_e32 v34, v55, v55
	v_fmac_f32_e32 v35, v36, v36
	v_fmac_f32_e32 v44, v38, v38
	v_add_f32_e32 v32, v32, v33
	v_mul_f32_e32 v33, v53, v53
	v_fmac_f32_e32 v34, v54, v54
	v_add_f32_e32 v35, v35, v44
	v_fmac_f32_e32 v33, v52, v52
	v_add_f32_e32 v34, v34, v35
	v_add_f32_e32 v33, v33, v34
	v_add_f32_e32 v35, v32, v33
	v_cvt_pk_bf16_f32 v41, v46, v47
	v_mov_b32_e32 v46, v35
	s_nop 1
	v_permlane16_swap_b32_e32 v46, v35
	v_lshl_add_u64 v[32:33], s[12:13], 0, v[218:219]
	v_lshl_add_u64 v[44:45], v[206:207], 1, v[32:33]
	v_cvt_pk_bf16_f32 v42, v50, v51
	v_cvt_pk_bf16_f32 v43, v48, v49
	s_waitcnt lgkmcnt(0)
	v_add_f32_e32 v32, v35, v46
	v_mov_b32_e32 v33, v32
	s_nop 1
	v_permlane32_swap_b32_e32 v33, v32
	global_store_dwordx4 v[44:45], v[40:43], off
	v_cvt_pk_bf16_f32 v34, v36, v37
	v_cvt_pk_bf16_f32 v35, v38, v39
	v_cvt_pk_bf16_f32 v36, v54, v55
	v_cvt_pk_bf16_f32 v37, v52, v53
	global_store_dwordx4 v[44:45], v[34:37], off offset:256
	s_and_saveexec_b64 s[38:39], s[4:5]
	s_cbranch_execz .LBB0_1027
	s_waitcnt lgkmcnt(0)
	v_add_f32_e32 v32, v32, v33
	v_mul_f32_e32 v32, 0x4b800000, v32
	v_trunc_f32_e32 v32, v32
	v_mul_f32_e32 v33, 0x2f800000, v32
	v_floor_f32_e32 v33, v33
	v_fmac_f32_e32 v32, 0xcf800000, v33
	v_cvt_u32_f32_e32 v32, v32
	v_cvt_u32_f32_e32 v33, v33
	v_lshl_add_u64 v[34:35], v[216:217], 3, s[14:15]
	global_atomic_add_x2 v[34:35], v[32:33], off
; __device__ __forceinline__ unsigned cvt_pk_bf16(float lo, float hi) { unsigned r; asm volatile("v_cvt_pk_bf16_f32 %0, %1, %2" : "=v"(r) : "v"(lo), "v"(hi)); return r; }
; __device__ __forceinline__ rss_t rss_fix(float ss) { return (rss_t)(ss * 16777216.0f); }
;     __device__ __forceinline__ void operator()(const f32x4 (&acc)[2][2][4][2], const Unit& u, int wr, int wc, int fr, int fq) const {
;     ...
;             for (int ai = 0; ai < 2; ++ai)
; #pragma unroll
;                 for (int m = 0; m < 4; ++m) {
;                     const int row = row0 + ai * HALF + m * 16; const size_t off = (size_t)row * 1024 + col0; float ss = 0.f;
; #pragma unroll
;                     for (int bj = 0; bj < 2; ++bj) { const u32x4 p = pre[ai][m][bj];
;                         const f32x4 b0 = {__uint_as_float(p.x << 16), __uint_as_float(p.x & 0xffff0000u), __uint_as_float(p.y << 16), __uint_as_float(p.y & 0xffff0000u)};
;                         const f32x4 b1 = {__uint_as_float(p.z << 16), __uint_as_float(p.z & 0xffff0000u), __uint_as_float(p.w << 16), __uint_as_float(p.w & 0xffff0000u)};
;                         const f32x4 v0 = b0 + acc[ai][bj][m][0] * alpha, v1 = b1 + acc[ai][bj][m][1] * alpha;
;                         store(off + bj * HALF, v0, v1, ss);
;                     }
;                     rowsum(row, ss, fq);
;                     if (m & 1) asm volatile("" ::: "memory");
;                 }
;         }
;     }
;     __device__ __forceinline__ void store(size_t o, const f32x4& v0, const f32x4& v1, float& ss) const {
;         if (out32) { *(f32x4*)(out32 + o) = v0; *(f32x4*)(out32 + o + 4) = v1; }
;         ss += (v0[0] * v0[0] + v0[1] * v0[1]) + (v0[2] * v0[2] + v0[3] * v0[3]) + (v1[0] * v1[0] + v1[1] * v1[1]) + (v1[2] * v1[2] + v1[3] * v1[3]);
;         if (hb) { u32x4 w; w.x = cvt_pk_bf16(v0[0], v0[1]); w.y = cvt_pk_bf16(v0[2], v0[3]); w.z = cvt_pk_bf16(v1[0], v1[1]); w.w = cvt_pk_bf16(v1[2], v1[3]); *(u32x4*)(hb + o) = w; }
;     }
;     __device__ __forceinline__ void rowsum(int row, float ss, int fq) const {
;         if (rowss_next) { ss += __shfl_xor(ss, 16); ss += __shfl_xor(ss, 32);
;             if (fq == 0) (void)__hip_atomic_fetch_add(rowss_next + row, rss_fix(ss), __ATOMIC_RELAXED, __HIP_MEMORY_SCOPE_AGENT); }
.LBB0_1027:
	s_or_b64 exec, exec, s[38:39]
	v_lshlrev_b32_e32 v32, 16, v120
	s_waitcnt lgkmcnt(0)
	v_and_b32_e32 v33, 0xffff0000, v120
	v_lshlrev_b32_e32 v34, 16, v121
	v_and_b32_e32 v35, 0xffff0000, v121
	v_lshlrev_b32_e32 v36, 16, v122
	v_and_b32_e32 v37, 0xffff0000, v122
	v_lshlrev_b32_e32 v38, 16, v123
	v_and_b32_e32 v39, 0xffff0000, v123
	v_pk_add_f32 v[30:31], v[30:31], v[34:35]
	v_pk_add_f32 v[28:29], v[28:29], v[32:33]
	v_pk_add_f32 v[34:35], v[24:25], v[36:37]
	v_lshlrev_b32_e32 v36, 16, v112
	v_and_b32_e32 v37, 0xffff0000, v112
	v_lshlrev_b32_e32 v42, 16, v115
	v_and_b32_e32 v43, 0xffff0000, v115
	v_pk_add_f32 v[32:33], v[26:27], v[38:39]
	v_lshlrev_b32_e32 v38, 16, v113
	v_and_b32_e32 v39, 0xffff0000, v113
	v_lshlrev_b32_e32 v40, 16, v114
	v_and_b32_e32 v41, 0xffff0000, v114
	v_pk_add_f32 v[20:21], v[20:21], v[36:37]
	v_pk_add_f32 v[36:37], v[18:19], v[42:43]
	v_mul_f32_e32 v18, v29, v29
	v_mul_f32_e32 v19, v31, v31
	v_pk_add_f32 v[22:23], v[22:23], v[38:39]
	v_pk_add_f32 v[38:39], v[16:17], v[40:41]
	v_mul_f32_e32 v17, v35, v35
	v_fmac_f32_e32 v18, v28, v28
	v_fmac_f32_e32 v19, v30, v30
	v_cvt_pk_bf16_f32 v24, v28, v29
	v_mul_f32_e32 v16, v33, v33
	v_fmac_f32_e32 v17, v34, v34
	v_add_f32_e32 v18, v18, v19
	v_mul_f32_e32 v19, v21, v21
	v_mul_f32_e32 v28, v23, v23
	v_fmac_f32_e32 v16, v32, v32
	v_add_f32_e32 v17, v17, v18
	v_mul_f32_e32 v18, v39, v39
	v_fmac_f32_e32 v19, v20, v20
	v_fmac_f32_e32 v28, v22, v22
	v_add_f32_e32 v16, v16, v17
	v_mul_f32_e32 v17, v37, v37
	v_fmac_f32_e32 v18, v38, v38
	v_add_f32_e32 v19, v19, v28
	v_fmac_f32_e32 v17, v36, v36
	v_add_f32_e32 v18, v18, v19
	v_add_f32_e32 v17, v17, v18
	v_add_f32_e32 v19, v16, v17
	v_cvt_pk_bf16_f32 v25, v30, v31
	v_mov_b32_e32 v30, v19
	s_nop 1
	v_permlane16_swap_b32_e32 v30, v19
	v_lshl_add_u64 v[16:17], s[12:13], 0, v[214:215]
	v_lshl_add_u64 v[28:29], v[206:207], 1, v[16:17]
	v_cvt_pk_bf16_f32 v26, v34, v35
	v_cvt_pk_bf16_f32 v27, v32, v33
	s_waitcnt lgkmcnt(0)
	v_add_f32_e32 v16, v19, v30
	v_mov_b32_e32 v17, v16
	s_nop 1
	v_permlane32_swap_b32_e32 v17, v16
	global_store_dwordx4 v[28:29], v[24:27], off
	v_cvt_pk_bf16_f32 v18, v20, v21
	v_cvt_pk_bf16_f32 v19, v22, v23
	v_cvt_pk_bf16_f32 v20, v38, v39
	v_cvt_pk_bf16_f32 v21, v36, v37
	global_store_dwordx4 v[28:29], v[18:21], off offset:256
	s_and_saveexec_b64 s[38:39], s[4:5]
	s_cbranch_execz .LBB0_1029
	s_waitcnt lgkmcnt(0)
	v_add_f32_e32 v16, v16, v17
	v_mul_f32_e32 v16, 0x4b800000, v16
	v_trunc_f32_e32 v16, v16
	v_mul_f32_e32 v17, 0x2f800000, v16
	v_floor_f32_e32 v17, v17
	v_fmac_f32_e32 v16, 0xcf800000, v17
	v_cvt_u32_f32_e32 v16, v16
	v_cvt_u32_f32_e32 v17, v17
	v_lshl_add_u64 v[18:19], v[212:213], 3, s[14:15]
	global_atomic_add_x2 v[18:19], v[16:17], off
.LBB0_1029:
	s_or_b64 exec, exec, s[38:39]
	v_lshlrev_b32_e32 v16, 16, v124
	s_waitcnt lgkmcnt(0)
	v_and_b32_e32 v17, 0xffff0000, v124
	v_lshlrev_b32_e32 v18, 16, v125
	v_and_b32_e32 v19, 0xffff0000, v125
	v_lshlrev_b32_e32 v20, 16, v126
	v_and_b32_e32 v21, 0xffff0000, v126
	v_lshlrev_b32_e32 v22, 16, v127
	v_and_b32_e32 v23, 0xffff0000, v127
	v_pk_add_f32 v[14:15], v[14:15], v[18:19]
	v_pk_add_f32 v[12:13], v[12:13], v[16:17]
	v_pk_add_f32 v[18:19], v[8:9], v[20:21]
	v_lshlrev_b32_e32 v20, 16, v116
	v_and_b32_e32 v21, 0xffff0000, v116
	v_lshlrev_b32_e32 v26, 16, v119
	v_and_b32_e32 v27, 0xffff0000, v119
	v_pk_add_f32 v[16:17], v[10:11], v[22:23]
	v_lshlrev_b32_e32 v22, 16, v117
	v_and_b32_e32 v23, 0xffff0000, v117
	v_lshlrev_b32_e32 v24, 16, v118
	v_and_b32_e32 v25, 0xffff0000, v118
	v_pk_add_f32 v[4:5], v[4:5], v[20:21]
	v_pk_add_f32 v[20:21], v[2:3], v[26:27]
	v_mul_f32_e32 v2, v13, v13
	v_mul_f32_e32 v3, v15, v15
	v_pk_add_f32 v[6:7], v[6:7], v[22:23]
	v_pk_add_f32 v[22:23], v[0:1], v[24:25]
	v_mul_f32_e32 v1, v19, v19
	v_fmac_f32_e32 v2, v12, v12
	v_fmac_f32_e32 v3, v14, v14
	v_cvt_pk_bf16_f32 v8, v12, v13
	v_mul_f32_e32 v0, v17, v17
	v_fmac_f32_e32 v1, v18, v18
	v_add_f32_e32 v2, v2, v3
	v_mul_f32_e32 v3, v5, v5
	v_mul_f32_e32 v12, v7, v7
	v_fmac_f32_e32 v0, v16, v16
	v_add_f32_e32 v1, v1, v2
	v_mul_f32_e32 v2, v23, v23
	v_fmac_f32_e32 v3, v4, v4
	v_fmac_f32_e32 v12, v6, v6
	v_add_f32_e32 v0, v0, v1
	v_mul_f32_e32 v1, v21, v21
	v_fmac_f32_e32 v2, v22, v22
	v_add_f32_e32 v3, v3, v12
	v_fmac_f32_e32 v1, v20, v20
	v_add_f32_e32 v2, v2, v3
	v_add_f32_e32 v1, v1, v2
	v_add_f32_e32 v3, v0, v1
	v_cvt_pk_bf16_f32 v9, v14, v15
	v_mov_b32_e32 v14, v3
	s_nop 1
	v_permlane16_swap_b32_e32 v14, v3
	v_lshl_add_u64 v[0:1], s[12:13], 0, v[210:211]
	v_lshl_add_u64 v[12:13], v[206:207], 1, v[0:1]
	v_cvt_pk_bf16_f32 v10, v18, v19
	v_cvt_pk_bf16_f32 v11, v16, v17
	s_waitcnt lgkmcnt(0)
	v_add_f32_e32 v0, v3, v14
	v_mov_b32_e32 v1, v0
	s_nop 1
	v_permlane32_swap_b32_e32 v1, v0
	global_store_dwordx4 v[12:13], v[8:11], off
	v_cvt_pk_bf16_f32 v2, v4, v5
	v_cvt_pk_bf16_f32 v3, v6, v7
	v_cvt_pk_bf16_f32 v4, v22, v23
	v_cvt_pk_bf16_f32 v5, v20, v21
	global_store_dwordx4 v[12:13], v[2:5], off offset:256
	s_and_saveexec_b64 s[38:39], s[4:5]
	s_cbranch_execz .LBB0_1031
	s_waitcnt lgkmcnt(0)
	v_add_f32_e32 v0, v0, v1
	v_mul_f32_e32 v0, 0x4b800000, v0
	v_trunc_f32_e32 v0, v0
	v_mul_f32_e32 v1, 0x2f800000, v0
	v_floor_f32_e32 v1, v1
	v_fmac_f32_e32 v0, 0xcf800000, v1
	v_cvt_u32_f32_e32 v0, v0
	v_cvt_u32_f32_e32 v1, v1
	v_lshl_add_u64 v[2:3], v[208:209], 3, s[14:15]
	global_atomic_add_x2 v[2:3], v[0:1], off
